# final phase hand-written (row pairs double-buffered, DPP+readlane row sums) on top of the interleaved scan
# baseline (speedup 1.0000x reference)
; __device__ void final_phase(const Params& p) {
;     ...
;     const float* modp = (const float*)(p.ws + WS_MODP);
;     const bf16_t* Y = (const bf16_t*)(p.ws + WS_QF);
;     const int rows_per = NLAT / gridDim.x;
;     for (int r0 = blockIdx.x * rows_per; r0 < NLAT; r0 += gridDim.x * rows_per) {
;         const int rend = min(r0 + rows_per, NLAT);
;         int curb = -1; f32x4 gt[4], g[4];
; #pragma unroll
;         for (int c = 0; c < 4; ++c) { g[c] = *(const f32x4*)(p.final_norm_g + c * 256 + lane * 4); gt[c] = (f32x4){0.f, 0.f, 0.f, 0.f}; }
;         for (int row = r0 + w * 2; row < rend; row += 16) {
;             const int b = row >> 12;
;             if (b != curb) { curb = b;
; #pragma unroll
;                 for (int c = 0; c < 4; ++c) { f32x4 t = *(const f32x4*)(p.b_mod + 2048 + c * 256 + lane * 4);
; #pragma unroll
;                     for (int q = 0; q < 4; ++q) t += *(const f32x4*)(modp + (q * 9 + b) * 3072 + 2048 + c * 256 + lane * 4);
;                     gt[c] = t; } }
;             const float* xp = p.x + (size_t)row * 1024; const bf16_t* yp = Y + (size_t)row * 1024; float* op = p.out + (size_t)row * 1024;
;             f32x4 h0[4], h1[4]; float s0 = 0.f, s1 = 0.f;
; #pragma unroll
;             for (int c = 0; c < 4; ++c) {
;                 const f32x4 x0 = *(const f32x4*)(xp + c * 256 + lane * 4), x1 = *(const f32x4*)(xp + 1024 + c * 256 + lane * 4);
;                 const u32x2 y0 = *(const u32x2*)(yp + c * 256 + lane * 4), y1 = *(const u32x2*)(yp + 1024 + c * 256 + lane * 4);
.LBB0_509:
	s_cmp_lt_i32 s72, 7
	s_cselect_b64 s[4:5], -1, 0
	s_and_b64 s[4:5], s[4:5], s[6:7]
	s_andn2_b64 vcc, exec, s[4:5]
	s_cbranch_vccnz .LBB0_518
	s_load_dword s3, s[0:1], 0x98
	s_waitcnt lgkmcnt(0)
	s_cmp_lg_u32 s3, 0x100
	s_cbranch_scc1 .Lp6_orig
	v_and_b32_e32 v1, 63, v0
	v_lshlrev_b32_e32 v170, 4, v1
	v_lshlrev_b32_e32 v171, 3, v1
	v_lshrrev_b32_e32 v1, 6, v0
	s_nop 0
	v_readfirstlane_b32 s10, v1
	s_lshl_b32 s3, s2, 7
	s_lshl_b32 s10, s10, 1
	s_add_u32 s3, s3, s10
	s_lshr_b32 s10, s2, 5
	s_mul_i32 s10, s10, 12288
	s_add_u32 s10, s10, 10493952
	s_add_u32 s4, s70, s10
	s_addc_u32 s5, s71, 0
	s_add_u32 s6, s48, 8192
	s_addc_u32 s7, s49, 0
	global_load_dwordx4 v[10:13], v170, s[6:7] offset:0
	global_load_dwordx4 v[14:17], v170, s[6:7] offset:1024
	global_load_dwordx4 v[18:21], v170, s[6:7] offset:2048
	global_load_dwordx4 v[22:25], v170, s[6:7] offset:3072
	global_load_dwordx4 v[42:45], v170, s[4:5] offset:0
	global_load_dwordx4 v[46:49], v170, s[4:5] offset:1024
	global_load_dwordx4 v[50:53], v170, s[4:5] offset:2048
	global_load_dwordx4 v[54:57], v170, s[4:5] offset:3072
	s_add_u32 s4, s4, 110592
	s_addc_u32 s5, s5, 0
	global_load_dwordx4 v[90:93], v170, s[4:5] offset:0
	global_load_dwordx4 v[94:97], v170, s[4:5] offset:1024
	global_load_dwordx4 v[98:101], v170, s[4:5] offset:2048
	global_load_dwordx4 v[102:105], v170, s[4:5] offset:3072
	s_add_u32 s4, s4, 110592
	s_addc_u32 s5, s5, 0
	global_load_dwordx4 v[58:61], v170, s[4:5] offset:0
	global_load_dwordx4 v[62:65], v170, s[4:5] offset:1024
	global_load_dwordx4 v[66:69], v170, s[4:5] offset:2048
	global_load_dwordx4 v[70:73], v170, s[4:5] offset:3072
	s_add_u32 s4, s4, 110592
	s_addc_u32 s5, s5, 0
	global_load_dwordx4 v[106:109], v170, s[4:5] offset:0
	global_load_dwordx4 v[110:113], v170, s[4:5] offset:1024
	global_load_dwordx4 v[114:117], v170, s[4:5] offset:2048
	global_load_dwordx4 v[118:121], v170, s[4:5] offset:3072
	global_load_dwordx4 v[26:29], v170, s[66:67] offset:0
	global_load_dwordx4 v[30:33], v170, s[66:67] offset:1024
	global_load_dwordx4 v[34:37], v170, s[66:67] offset:2048
	global_load_dwordx4 v[38:41], v170, s[66:67] offset:3072
	s_waitcnt vmcnt(0)
	v_add_f32_e32 v10, v10, v42
	v_add_f32_e32 v11, v11, v43
	v_add_f32_e32 v12, v12, v44
	v_add_f32_e32 v13, v13, v45
	v_add_f32_e32 v14, v14, v46
	v_add_f32_e32 v15, v15, v47
	v_add_f32_e32 v16, v16, v48
	v_add_f32_e32 v17, v17, v49
	v_add_f32_e32 v18, v18, v50
	v_add_f32_e32 v19, v19, v51
	v_add_f32_e32 v20, v20, v52
	v_add_f32_e32 v21, v21, v53
	v_add_f32_e32 v22, v22, v54
	v_add_f32_e32 v23, v23, v55
	v_add_f32_e32 v24, v24, v56
	v_add_f32_e32 v25, v25, v57
	v_add_f32_e32 v10, v10, v90
	v_add_f32_e32 v11, v11, v91
	v_add_f32_e32 v12, v12, v92
	v_add_f32_e32 v13, v13, v93
	v_add_f32_e32 v14, v14, v94
	v_add_f32_e32 v15, v15, v95
	v_add_f32_e32 v16, v16, v96
	v_add_f32_e32 v17, v17, v97
	v_add_f32_e32 v18, v18, v98
	v_add_f32_e32 v19, v19, v99
	v_add_f32_e32 v20, v20, v100
	v_add_f32_e32 v21, v21, v101
	v_add_f32_e32 v22, v22, v102
	v_add_f32_e32 v23, v23, v103
	v_add_f32_e32 v24, v24, v104
	v_add_f32_e32 v25, v25, v105
	v_add_f32_e32 v10, v10, v58
	v_add_f32_e32 v11, v11, v59
	v_add_f32_e32 v12, v12, v60
	v_add_f32_e32 v13, v13, v61
	v_add_f32_e32 v14, v14, v62
	v_add_f32_e32 v15, v15, v63
	v_add_f32_e32 v16, v16, v64
	v_add_f32_e32 v17, v17, v65
	v_add_f32_e32 v18, v18, v66
	v_add_f32_e32 v19, v19, v67
	v_add_f32_e32 v20, v20, v68
	v_add_f32_e32 v21, v21, v69
	v_add_f32_e32 v22, v22, v70
	v_add_f32_e32 v23, v23, v71
	v_add_f32_e32 v24, v24, v72
	v_add_f32_e32 v25, v25, v73
	v_add_f32_e32 v10, v10, v106
	v_add_f32_e32 v11, v11, v107
	v_add_f32_e32 v12, v12, v108
	v_add_f32_e32 v13, v13, v109
	v_add_f32_e32 v14, v14, v110
	v_add_f32_e32 v15, v15, v111
	v_add_f32_e32 v16, v16, v112
	v_add_f32_e32 v17, v17, v113
	v_add_f32_e32 v18, v18, v114
	v_add_f32_e32 v19, v19, v115
	v_add_f32_e32 v20, v20, v116
	v_add_f32_e32 v21, v21, v117
	v_add_f32_e32 v22, v22, v118
	v_add_f32_e32 v23, v23, v119
	v_add_f32_e32 v24, v24, v120
	v_add_f32_e32 v25, v25, v121
	s_add_u32 s10, s3, 0
	s_lshl_b32 s11, s10, 12
	s_add_u32 s4, s36, s11
	s_addc_u32 s5, s37, 0
	s_lshl_b32 s11, s10, 11
	s_add_u32 s11, s11, 0x5100000
	s_add_u32 s6, s70, s11
	s_addc_u32 s7, s71, 0
	global_load_dwordx4 v[42:45], v170, s[4:5] offset:0
	global_load_dwordx4 v[46:49], v170, s[4:5] offset:1024
	global_load_dwordx4 v[50:53], v170, s[4:5] offset:2048
	global_load_dwordx4 v[54:57], v170, s[4:5] offset:3072
	global_load_dwordx2 v[74:75], v171, s[6:7] offset:0
	global_load_dwordx2 v[76:77], v171, s[6:7] offset:512
	global_load_dwordx2 v[78:79], v171, s[6:7] offset:1024
	global_load_dwordx2 v[80:81], v171, s[6:7] offset:1536
	s_add_u32 s4, s4, 0x1000
	s_addc_u32 s5, s5, 0
	s_add_u32 s6, s6, 0x800
	s_addc_u32 s7, s7, 0
	global_load_dwordx4 v[58:61], v170, s[4:5] offset:0
	global_load_dwordx4 v[62:65], v170, s[4:5] offset:1024
	global_load_dwordx4 v[66:69], v170, s[4:5] offset:2048
	global_load_dwordx4 v[70:73], v170, s[4:5] offset:3072
	global_load_dwordx2 v[82:83], v171, s[6:7] offset:0
	global_load_dwordx2 v[84:85], v171, s[6:7] offset:512
	global_load_dwordx2 v[86:87], v171, s[6:7] offset:1024
	global_load_dwordx2 v[88:89], v171, s[6:7] offset:1536
	s_add_u32 s10, s3, 16
	s_lshl_b32 s11, s10, 12
	s_add_u32 s4, s36, s11
	s_addc_u32 s5, s37, 0
	s_lshl_b32 s11, s10, 11
	s_add_u32 s11, s11, 0x5100000
	s_add_u32 s6, s70, s11
	s_addc_u32 s7, s71, 0
	global_load_dwordx4 v[90:93], v170, s[4:5] offset:0
	global_load_dwordx4 v[94:97], v170, s[4:5] offset:1024
	global_load_dwordx4 v[98:101], v170, s[4:5] offset:2048
	global_load_dwordx4 v[102:105], v170, s[4:5] offset:3072
	global_load_dwordx2 v[122:123], v171, s[6:7] offset:0
	global_load_dwordx2 v[124:125], v171, s[6:7] offset:512
	global_load_dwordx2 v[126:127], v171, s[6:7] offset:1024
	global_load_dwordx2 v[128:129], v171, s[6:7] offset:1536
	s_add_u32 s4, s4, 0x1000
	s_addc_u32 s5, s5, 0
	s_add_u32 s6, s6, 0x800
	s_addc_u32 s7, s7, 0
	global_load_dwordx4 v[106:109], v170, s[4:5] offset:0
	global_load_dwordx4 v[110:113], v170, s[4:5] offset:1024
	global_load_dwordx4 v[114:117], v170, s[4:5] offset:2048
	global_load_dwordx4 v[118:121], v170, s[4:5] offset:3072
	global_load_dwordx2 v[130:131], v171, s[6:7] offset:0
	global_load_dwordx2 v[132:133], v171, s[6:7] offset:512
	global_load_dwordx2 v[134:135], v171, s[6:7] offset:1024
	global_load_dwordx2 v[136:137], v171, s[6:7] offset:1536
	s_waitcnt vmcnt(16)
; __device__ __forceinline__ float bf_lo(unsigned u) { return __uint_as_float(u << 16); }
; __device__ __forceinline__ float bf_hi(unsigned u) { return __uint_as_float(u & 0xffff0000u); }
; __device__ void final_phase(const Params& p) {
;     ...
;             for (int c = 0; c < 4; ++c) {
;                 const f32x4 x0 = *(const f32x4*)(xp + c * 256 + lane * 4), x1 = *(const f32x4*)(xp + 1024 + c * 256 + lane * 4);
;                 const u32x2 y0 = *(const u32x2*)(yp + c * 256 + lane * 4), y1 = *(const u32x2*)(yp + 1024 + c * 256 + lane * 4);
;                 h0[c] = x0 + gt[c] * (f32x4){bf_lo(y0[0]), bf_hi(y0[0]), bf_lo(y0[1]), bf_hi(y0[1])};
;                 h1[c] = x1 + gt[c] * (f32x4){bf_lo(y1[0]), bf_hi(y1[0]), bf_lo(y1[1]), bf_hi(y1[1])};
;                 s0 += h0[c][0] * h0[c][0] + h0[c][1] * h0[c][1] + h0[c][2] * h0[c][2] + h0[c][3] * h0[c][3];
;                 s1 += h1[c][0] * h1[c][0] + h1[c][1] * h1[c][1] + h1[c][2] * h1[c][2] + h1[c][3] * h1[c][3];
;             }
; #pragma unroll
;             for (int m = 32; m >= 1; m >>= 1) { s0 += __shfl_xor(s0, m); s1 += __shfl_xor(s1, m); }
;             const float rs0 = rsqrtf(s0 * (1.f / 1024.f) + EPS), rs1 = rsqrtf(s1 * (1.f / 1024.f) + EPS);
; #pragma unroll
;             for (int c = 0; c < 4; ++c) { *(f32x4*)(op + c * 256 + lane * 4) = h0[c] * rs0 * g[c]; *(f32x4*)(op + 1024 + c * 256 + lane * 4) = h1[c] * rs1 * g[c]; }
	v_lshlrev_b32_e32 v174, 16, v74
	v_fma_f32 v138, v10, v174, v42
	v_and_b32_e32 v174, 0xffff0000, v74
	v_fma_f32 v139, v11, v174, v43
	v_lshlrev_b32_e32 v174, 16, v75
	v_fma_f32 v140, v12, v174, v44
	v_and_b32_e32 v174, 0xffff0000, v75
	v_fma_f32 v141, v13, v174, v45
	v_lshlrev_b32_e32 v174, 16, v76
	v_fma_f32 v142, v14, v174, v46
	v_and_b32_e32 v174, 0xffff0000, v76
	v_fma_f32 v143, v15, v174, v47
	v_lshlrev_b32_e32 v174, 16, v77
	v_fma_f32 v144, v16, v174, v48
	v_and_b32_e32 v174, 0xffff0000, v77
	v_fma_f32 v145, v17, v174, v49
	v_lshlrev_b32_e32 v174, 16, v78
	v_fma_f32 v146, v18, v174, v50
	v_and_b32_e32 v174, 0xffff0000, v78
	v_fma_f32 v147, v19, v174, v51
	v_lshlrev_b32_e32 v174, 16, v79
	v_fma_f32 v148, v20, v174, v52
	v_and_b32_e32 v174, 0xffff0000, v79
	v_fma_f32 v149, v21, v174, v53
	v_lshlrev_b32_e32 v174, 16, v80
	v_fma_f32 v150, v22, v174, v54
	v_and_b32_e32 v174, 0xffff0000, v80
	v_fma_f32 v151, v23, v174, v55
	v_lshlrev_b32_e32 v174, 16, v81
	v_fma_f32 v152, v24, v174, v56
	v_and_b32_e32 v174, 0xffff0000, v81
	v_fma_f32 v153, v25, v174, v57
	v_mul_f32_e32 v172, v138, v138
	v_fmac_f32_e32 v172, v139, v139
	v_fmac_f32_e32 v172, v140, v140
	v_fmac_f32_e32 v172, v141, v141
	v_fmac_f32_e32 v172, v142, v142
	v_fmac_f32_e32 v172, v143, v143
	v_fmac_f32_e32 v172, v144, v144
	v_fmac_f32_e32 v172, v145, v145
	v_fmac_f32_e32 v172, v146, v146
	v_fmac_f32_e32 v172, v147, v147
	v_fmac_f32_e32 v172, v148, v148
	v_fmac_f32_e32 v172, v149, v149
	v_fmac_f32_e32 v172, v150, v150
	v_fmac_f32_e32 v172, v151, v151
	v_fmac_f32_e32 v172, v152, v152
	v_fmac_f32_e32 v172, v153, v153
	v_lshlrev_b32_e32 v174, 16, v82
	v_fma_f32 v154, v10, v174, v58
	v_and_b32_e32 v174, 0xffff0000, v82
	v_fma_f32 v155, v11, v174, v59
	v_lshlrev_b32_e32 v174, 16, v83
	v_fma_f32 v156, v12, v174, v60
	v_and_b32_e32 v174, 0xffff0000, v83
	v_fma_f32 v157, v13, v174, v61
	v_lshlrev_b32_e32 v174, 16, v84
	v_fma_f32 v158, v14, v174, v62
	v_and_b32_e32 v174, 0xffff0000, v84
	v_fma_f32 v159, v15, v174, v63
	v_lshlrev_b32_e32 v174, 16, v85
	v_fma_f32 v160, v16, v174, v64
	v_and_b32_e32 v174, 0xffff0000, v85
	v_fma_f32 v161, v17, v174, v65
	v_lshlrev_b32_e32 v174, 16, v86
	v_fma_f32 v162, v18, v174, v66
	v_and_b32_e32 v174, 0xffff0000, v86
	v_fma_f32 v163, v19, v174, v67
	v_lshlrev_b32_e32 v174, 16, v87
	v_fma_f32 v164, v20, v174, v68
	v_and_b32_e32 v174, 0xffff0000, v87
	v_fma_f32 v165, v21, v174, v69
	v_lshlrev_b32_e32 v174, 16, v88
	v_fma_f32 v166, v22, v174, v70
	v_and_b32_e32 v174, 0xffff0000, v88
	v_fma_f32 v167, v23, v174, v71
	v_lshlrev_b32_e32 v174, 16, v89
	v_fma_f32 v168, v24, v174, v72
	v_and_b32_e32 v174, 0xffff0000, v89
	v_fma_f32 v169, v25, v174, v73
	v_mul_f32_e32 v173, v154, v154
	v_fmac_f32_e32 v173, v155, v155
	v_fmac_f32_e32 v173, v156, v156
	v_fmac_f32_e32 v173, v157, v157
	v_fmac_f32_e32 v173, v158, v158
	v_fmac_f32_e32 v173, v159, v159
	v_fmac_f32_e32 v173, v160, v160
	v_fmac_f32_e32 v173, v161, v161
	v_fmac_f32_e32 v173, v162, v162
	v_fmac_f32_e32 v173, v163, v163
	v_fmac_f32_e32 v173, v164, v164
	v_fmac_f32_e32 v173, v165, v165
	v_fmac_f32_e32 v173, v166, v166
	v_fmac_f32_e32 v173, v167, v167
	v_fmac_f32_e32 v173, v168, v168
	v_fmac_f32_e32 v173, v169, v169
	s_nop 1
	v_add_f32_dpp v172, v172, v172 row_shr:1 row_mask:0xf bank_mask:0xf bound_ctrl:1
	s_nop 1
	v_add_f32_dpp v173, v173, v173 row_shr:1 row_mask:0xf bank_mask:0xf bound_ctrl:1
	s_nop 0
	v_add_f32_dpp v172, v172, v172 row_shr:2 row_mask:0xf bank_mask:0xf bound_ctrl:1
	v_add_f32_dpp v173, v173, v173 row_shr:2 row_mask:0xf bank_mask:0xf bound_ctrl:1
	s_nop 0
	v_add_f32_dpp v172, v172, v172 row_shr:4 row_mask:0xf bank_mask:0xf bound_ctrl:1
	v_add_f32_dpp v173, v173, v173 row_shr:4 row_mask:0xf bank_mask:0xf bound_ctrl:1
	s_nop 0
	v_add_f32_dpp v172, v172, v172 row_shr:8 row_mask:0xf bank_mask:0xf bound_ctrl:1
	v_add_f32_dpp v173, v173, v173 row_shr:8 row_mask:0xf bank_mask:0xf bound_ctrl:1
	s_nop 0
	v_readlane_b32 s12, v172, 15
	v_readlane_b32 s13, v172, 31
	v_readlane_b32 s14, v172, 47
	v_readlane_b32 s15, v172, 63
	v_readlane_b32 s16, v173, 15
	v_readlane_b32 s17, v173, 31
	v_readlane_b32 s18, v173, 47
	v_readlane_b32 s19, v173, 63
	s_nop 1
	v_mov_b32_e32 v172, s12
	v_add_f32_e32 v172, s13, v172
	v_add_f32_e32 v172, s14, v172
	v_add_f32_e32 v172, s15, v172
	v_mov_b32_e32 v173, s16
	v_add_f32_e32 v173, s17, v173
	v_add_f32_e32 v173, s18, v173
	v_add_f32_e32 v173, s19, v173
	v_mov_b32_e32 v174, 0x358637bd
	v_fmac_f32_e32 v174, 0x3a800000, v172
	v_rsq_f32_e32 v172, v174
	v_mov_b32_e32 v174, 0x358637bd
	v_fmac_f32_e32 v174, 0x3a800000, v173
	v_rsq_f32_e32 v173, v174
	s_nop 0
	v_mul_f32_e32 v138, v138, v172
	v_mul_f32_e32 v139, v139, v172
	v_mul_f32_e32 v140, v140, v172
	v_mul_f32_e32 v141, v141, v172
	v_mul_f32_e32 v142, v142, v172
	v_mul_f32_e32 v143, v143, v172
	v_mul_f32_e32 v144, v144, v172
	v_mul_f32_e32 v145, v145, v172
	v_mul_f32_e32 v146, v146, v172
	v_mul_f32_e32 v147, v147, v172
	v_mul_f32_e32 v148, v148, v172
	v_mul_f32_e32 v149, v149, v172
	v_mul_f32_e32 v150, v150, v172
	v_mul_f32_e32 v151, v151, v172
	v_mul_f32_e32 v152, v152, v172
	v_mul_f32_e32 v153, v153, v172
	v_mul_f32_e32 v138, v26, v138
	v_mul_f32_e32 v139, v27, v139
	v_mul_f32_e32 v140, v28, v140
	v_mul_f32_e32 v141, v29, v141
	v_mul_f32_e32 v142, v30, v142
	v_mul_f32_e32 v143, v31, v143
	v_mul_f32_e32 v144, v32, v144
	v_mul_f32_e32 v145, v33, v145
	v_mul_f32_e32 v146, v34, v146
	v_mul_f32_e32 v147, v35, v147
	v_mul_f32_e32 v148, v36, v148
	v_mul_f32_e32 v149, v37, v149
	v_mul_f32_e32 v150, v38, v150
	v_mul_f32_e32 v151, v39, v151
	v_mul_f32_e32 v152, v40, v152
	v_mul_f32_e32 v153, v41, v153
	v_mul_f32_e32 v154, v154, v173
; __device__ __forceinline__ float bf_lo(unsigned u) { return __uint_as_float(u << 16); }
; __device__ __forceinline__ float bf_hi(unsigned u) { return __uint_as_float(u & 0xffff0000u); }
; __device__ void final_phase(const Params& p) {
;     ...
;             const float* xp = p.x + (size_t)row * 1024; const bf16_t* yp = Y + (size_t)row * 1024; float* op = p.out + (size_t)row * 1024;
;             f32x4 h0[4], h1[4]; float s0 = 0.f, s1 = 0.f;
; #pragma unroll
;             for (int c = 0; c < 4; ++c) {
;                 const f32x4 x0 = *(const f32x4*)(xp + c * 256 + lane * 4), x1 = *(const f32x4*)(xp + 1024 + c * 256 + lane * 4);
;                 const u32x2 y0 = *(const u32x2*)(yp + c * 256 + lane * 4), y1 = *(const u32x2*)(yp + 1024 + c * 256 + lane * 4);
;                 h0[c] = x0 + gt[c] * (f32x4){bf_lo(y0[0]), bf_hi(y0[0]), bf_lo(y0[1]), bf_hi(y0[1])};
;                 h1[c] = x1 + gt[c] * (f32x4){bf_lo(y1[0]), bf_hi(y1[0]), bf_lo(y1[1]), bf_hi(y1[1])};
;                 s0 += h0[c][0] * h0[c][0] + h0[c][1] * h0[c][1] + h0[c][2] * h0[c][2] + h0[c][3] * h0[c][3];
;                 s1 += h1[c][0] * h1[c][0] + h1[c][1] * h1[c][1] + h1[c][2] * h1[c][2] + h1[c][3] * h1[c][3];
;             }
; #pragma unroll
;             for (int m = 32; m >= 1; m >>= 1) { s0 += __shfl_xor(s0, m); s1 += __shfl_xor(s1, m); }
;             const float rs0 = rsqrtf(s0 * (1.f / 1024.f) + EPS), rs1 = rsqrtf(s1 * (1.f / 1024.f) + EPS);
; #pragma unroll
;             for (int c = 0; c < 4; ++c) { *(f32x4*)(op + c * 256 + lane * 4) = h0[c] * rs0 * g[c]; *(f32x4*)(op + 1024 + c * 256 + lane * 4) = h1[c] * rs1 * g[c]; }
	v_mul_f32_e32 v155, v155, v173
	v_mul_f32_e32 v156, v156, v173
	v_mul_f32_e32 v157, v157, v173
	v_mul_f32_e32 v158, v158, v173
	v_mul_f32_e32 v159, v159, v173
	v_mul_f32_e32 v160, v160, v173
	v_mul_f32_e32 v161, v161, v173
	v_mul_f32_e32 v162, v162, v173
	v_mul_f32_e32 v163, v163, v173
	v_mul_f32_e32 v164, v164, v173
	v_mul_f32_e32 v165, v165, v173
	v_mul_f32_e32 v166, v166, v173
	v_mul_f32_e32 v167, v167, v173
	v_mul_f32_e32 v168, v168, v173
	v_mul_f32_e32 v169, v169, v173
	v_mul_f32_e32 v154, v26, v154
	v_mul_f32_e32 v155, v27, v155
	v_mul_f32_e32 v156, v28, v156
	v_mul_f32_e32 v157, v29, v157
	v_mul_f32_e32 v158, v30, v158
	v_mul_f32_e32 v159, v31, v159
	v_mul_f32_e32 v160, v32, v160
	v_mul_f32_e32 v161, v33, v161
	v_mul_f32_e32 v162, v34, v162
	v_mul_f32_e32 v163, v35, v163
	v_mul_f32_e32 v164, v36, v164
	v_mul_f32_e32 v165, v37, v165
	v_mul_f32_e32 v166, v38, v166
	v_mul_f32_e32 v167, v39, v167
	v_mul_f32_e32 v168, v40, v168
	v_mul_f32_e32 v169, v41, v169
	s_add_u32 s10, s3, 0
	s_lshl_b32 s11, s10, 12
	s_add_u32 s8, s68, s11
	s_addc_u32 s9, s69, 0
	global_store_dwordx4 v170, v[138:141], s[8:9] offset:0
	global_store_dwordx4 v170, v[142:145], s[8:9] offset:1024
	global_store_dwordx4 v170, v[146:149], s[8:9] offset:2048
	global_store_dwordx4 v170, v[150:153], s[8:9] offset:3072
	s_add_u32 s8, s8, 0x1000
	s_addc_u32 s9, s9, 0
	global_store_dwordx4 v170, v[154:157], s[8:9] offset:0
	global_store_dwordx4 v170, v[158:161], s[8:9] offset:1024
	global_store_dwordx4 v170, v[162:165], s[8:9] offset:2048
	global_store_dwordx4 v170, v[166:169], s[8:9] offset:3072
	s_add_u32 s10, s3, 32
	s_lshl_b32 s11, s10, 12
	s_add_u32 s4, s36, s11
	s_addc_u32 s5, s37, 0
	s_lshl_b32 s11, s10, 11
	s_add_u32 s11, s11, 0x5100000
	s_add_u32 s6, s70, s11
	s_addc_u32 s7, s71, 0
	global_load_dwordx4 v[42:45], v170, s[4:5] offset:0
	global_load_dwordx4 v[46:49], v170, s[4:5] offset:1024
	global_load_dwordx4 v[50:53], v170, s[4:5] offset:2048
	global_load_dwordx4 v[54:57], v170, s[4:5] offset:3072
	global_load_dwordx2 v[74:75], v171, s[6:7] offset:0
	global_load_dwordx2 v[76:77], v171, s[6:7] offset:512
	global_load_dwordx2 v[78:79], v171, s[6:7] offset:1024
	global_load_dwordx2 v[80:81], v171, s[6:7] offset:1536
	s_add_u32 s4, s4, 0x1000
	s_addc_u32 s5, s5, 0
	s_add_u32 s6, s6, 0x800
	s_addc_u32 s7, s7, 0
	global_load_dwordx4 v[58:61], v170, s[4:5] offset:0
	global_load_dwordx4 v[62:65], v170, s[4:5] offset:1024
	global_load_dwordx4 v[66:69], v170, s[4:5] offset:2048
	global_load_dwordx4 v[70:73], v170, s[4:5] offset:3072
	global_load_dwordx2 v[82:83], v171, s[6:7] offset:0
	global_load_dwordx2 v[84:85], v171, s[6:7] offset:512
	global_load_dwordx2 v[86:87], v171, s[6:7] offset:1024
	global_load_dwordx2 v[88:89], v171, s[6:7] offset:1536
	s_waitcnt vmcnt(24)
	v_lshlrev_b32_e32 v174, 16, v122
	v_fma_f32 v138, v10, v174, v90
	v_and_b32_e32 v174, 0xffff0000, v122
	v_fma_f32 v139, v11, v174, v91
	v_lshlrev_b32_e32 v174, 16, v123
	v_fma_f32 v140, v12, v174, v92
	v_and_b32_e32 v174, 0xffff0000, v123
	v_fma_f32 v141, v13, v174, v93
	v_lshlrev_b32_e32 v174, 16, v124
	v_fma_f32 v142, v14, v174, v94
	v_and_b32_e32 v174, 0xffff0000, v124
	v_fma_f32 v143, v15, v174, v95
	v_lshlrev_b32_e32 v174, 16, v125
	v_fma_f32 v144, v16, v174, v96
	v_and_b32_e32 v174, 0xffff0000, v125
	v_fma_f32 v145, v17, v174, v97
	v_lshlrev_b32_e32 v174, 16, v126
	v_fma_f32 v146, v18, v174, v98
	v_and_b32_e32 v174, 0xffff0000, v126
	v_fma_f32 v147, v19, v174, v99
	v_lshlrev_b32_e32 v174, 16, v127
	v_fma_f32 v148, v20, v174, v100
	v_and_b32_e32 v174, 0xffff0000, v127
	v_fma_f32 v149, v21, v174, v101
	v_lshlrev_b32_e32 v174, 16, v128
	v_fma_f32 v150, v22, v174, v102
	v_and_b32_e32 v174, 0xffff0000, v128
	v_fma_f32 v151, v23, v174, v103
	v_lshlrev_b32_e32 v174, 16, v129
	v_fma_f32 v152, v24, v174, v104
	v_and_b32_e32 v174, 0xffff0000, v129
	v_fma_f32 v153, v25, v174, v105
	v_mul_f32_e32 v172, v138, v138
	v_fmac_f32_e32 v172, v139, v139
	v_fmac_f32_e32 v172, v140, v140
	v_fmac_f32_e32 v172, v141, v141
	v_fmac_f32_e32 v172, v142, v142
	v_fmac_f32_e32 v172, v143, v143
	v_fmac_f32_e32 v172, v144, v144
	v_fmac_f32_e32 v172, v145, v145
	v_fmac_f32_e32 v172, v146, v146
	v_fmac_f32_e32 v172, v147, v147
	v_fmac_f32_e32 v172, v148, v148
	v_fmac_f32_e32 v172, v149, v149
	v_fmac_f32_e32 v172, v150, v150
	v_fmac_f32_e32 v172, v151, v151
	v_fmac_f32_e32 v172, v152, v152
	v_fmac_f32_e32 v172, v153, v153
	v_lshlrev_b32_e32 v174, 16, v130
	v_fma_f32 v154, v10, v174, v106
	v_and_b32_e32 v174, 0xffff0000, v130
	v_fma_f32 v155, v11, v174, v107
	v_lshlrev_b32_e32 v174, 16, v131
	v_fma_f32 v156, v12, v174, v108
	v_and_b32_e32 v174, 0xffff0000, v131
	v_fma_f32 v157, v13, v174, v109
	v_lshlrev_b32_e32 v174, 16, v132
	v_fma_f32 v158, v14, v174, v110
	v_and_b32_e32 v174, 0xffff0000, v132
	v_fma_f32 v159, v15, v174, v111
	v_lshlrev_b32_e32 v174, 16, v133
	v_fma_f32 v160, v16, v174, v112
	v_and_b32_e32 v174, 0xffff0000, v133
	v_fma_f32 v161, v17, v174, v113
	v_lshlrev_b32_e32 v174, 16, v134
	v_fma_f32 v162, v18, v174, v114
	v_and_b32_e32 v174, 0xffff0000, v134
	v_fma_f32 v163, v19, v174, v115
	v_lshlrev_b32_e32 v174, 16, v135
	v_fma_f32 v164, v20, v174, v116
	v_and_b32_e32 v174, 0xffff0000, v135
	v_fma_f32 v165, v21, v174, v117
	v_lshlrev_b32_e32 v174, 16, v136
	v_fma_f32 v166, v22, v174, v118
	v_and_b32_e32 v174, 0xffff0000, v136
	v_fma_f32 v167, v23, v174, v119
	v_lshlrev_b32_e32 v174, 16, v137
	v_fma_f32 v168, v24, v174, v120
	v_and_b32_e32 v174, 0xffff0000, v137
	v_fma_f32 v169, v25, v174, v121
	v_mul_f32_e32 v173, v154, v154
	v_fmac_f32_e32 v173, v155, v155
	v_fmac_f32_e32 v173, v156, v156
	v_fmac_f32_e32 v173, v157, v157
; __device__ void final_phase(const Params& p) {
;     ...
;                 s0 += h0[c][0] * h0[c][0] + h0[c][1] * h0[c][1] + h0[c][2] * h0[c][2] + h0[c][3] * h0[c][3];
;                 s1 += h1[c][0] * h1[c][0] + h1[c][1] * h1[c][1] + h1[c][2] * h1[c][2] + h1[c][3] * h1[c][3];
;             }
; #pragma unroll
;             for (int m = 32; m >= 1; m >>= 1) { s0 += __shfl_xor(s0, m); s1 += __shfl_xor(s1, m); }
;             const float rs0 = rsqrtf(s0 * (1.f / 1024.f) + EPS), rs1 = rsqrtf(s1 * (1.f / 1024.f) + EPS);
; #pragma unroll
;             for (int c = 0; c < 4; ++c) { *(f32x4*)(op + c * 256 + lane * 4) = h0[c] * rs0 * g[c]; *(f32x4*)(op + 1024 + c * 256 + lane * 4) = h1[c] * rs1 * g[c]; }
	v_fmac_f32_e32 v173, v158, v158
	v_fmac_f32_e32 v173, v159, v159
	v_fmac_f32_e32 v173, v160, v160
	v_fmac_f32_e32 v173, v161, v161
	v_fmac_f32_e32 v173, v162, v162
	v_fmac_f32_e32 v173, v163, v163
	v_fmac_f32_e32 v173, v164, v164
	v_fmac_f32_e32 v173, v165, v165
	v_fmac_f32_e32 v173, v166, v166
	v_fmac_f32_e32 v173, v167, v167
	v_fmac_f32_e32 v173, v168, v168
	v_fmac_f32_e32 v173, v169, v169
	s_nop 1
	v_add_f32_dpp v172, v172, v172 row_shr:1 row_mask:0xf bank_mask:0xf bound_ctrl:1
	s_nop 1
	v_add_f32_dpp v173, v173, v173 row_shr:1 row_mask:0xf bank_mask:0xf bound_ctrl:1
	s_nop 0
	v_add_f32_dpp v172, v172, v172 row_shr:2 row_mask:0xf bank_mask:0xf bound_ctrl:1
	v_add_f32_dpp v173, v173, v173 row_shr:2 row_mask:0xf bank_mask:0xf bound_ctrl:1
	s_nop 0
	v_add_f32_dpp v172, v172, v172 row_shr:4 row_mask:0xf bank_mask:0xf bound_ctrl:1
	v_add_f32_dpp v173, v173, v173 row_shr:4 row_mask:0xf bank_mask:0xf bound_ctrl:1
	s_nop 0
	v_add_f32_dpp v172, v172, v172 row_shr:8 row_mask:0xf bank_mask:0xf bound_ctrl:1
	v_add_f32_dpp v173, v173, v173 row_shr:8 row_mask:0xf bank_mask:0xf bound_ctrl:1
	s_nop 0
	v_readlane_b32 s12, v172, 15
	v_readlane_b32 s13, v172, 31
	v_readlane_b32 s14, v172, 47
	v_readlane_b32 s15, v172, 63
	v_readlane_b32 s16, v173, 15
	v_readlane_b32 s17, v173, 31
	v_readlane_b32 s18, v173, 47
	v_readlane_b32 s19, v173, 63
	s_nop 1
	v_mov_b32_e32 v172, s12
	v_add_f32_e32 v172, s13, v172
	v_add_f32_e32 v172, s14, v172
	v_add_f32_e32 v172, s15, v172
	v_mov_b32_e32 v173, s16
	v_add_f32_e32 v173, s17, v173
	v_add_f32_e32 v173, s18, v173
	v_add_f32_e32 v173, s19, v173
	v_mov_b32_e32 v174, 0x358637bd
	v_fmac_f32_e32 v174, 0x3a800000, v172
	v_rsq_f32_e32 v172, v174
	v_mov_b32_e32 v174, 0x358637bd
	v_fmac_f32_e32 v174, 0x3a800000, v173
	v_rsq_f32_e32 v173, v174
	s_nop 0
	v_mul_f32_e32 v138, v138, v172
	v_mul_f32_e32 v139, v139, v172
	v_mul_f32_e32 v140, v140, v172
	v_mul_f32_e32 v141, v141, v172
	v_mul_f32_e32 v142, v142, v172
	v_mul_f32_e32 v143, v143, v172
	v_mul_f32_e32 v144, v144, v172
	v_mul_f32_e32 v145, v145, v172
	v_mul_f32_e32 v146, v146, v172
	v_mul_f32_e32 v147, v147, v172
	v_mul_f32_e32 v148, v148, v172
	v_mul_f32_e32 v149, v149, v172
	v_mul_f32_e32 v150, v150, v172
	v_mul_f32_e32 v151, v151, v172
	v_mul_f32_e32 v152, v152, v172
	v_mul_f32_e32 v153, v153, v172
	v_mul_f32_e32 v138, v26, v138
	v_mul_f32_e32 v139, v27, v139
	v_mul_f32_e32 v140, v28, v140
	v_mul_f32_e32 v141, v29, v141
	v_mul_f32_e32 v142, v30, v142
	v_mul_f32_e32 v143, v31, v143
	v_mul_f32_e32 v144, v32, v144
	v_mul_f32_e32 v145, v33, v145
	v_mul_f32_e32 v146, v34, v146
	v_mul_f32_e32 v147, v35, v147
	v_mul_f32_e32 v148, v36, v148
	v_mul_f32_e32 v149, v37, v149
	v_mul_f32_e32 v150, v38, v150
	v_mul_f32_e32 v151, v39, v151
	v_mul_f32_e32 v152, v40, v152
	v_mul_f32_e32 v153, v41, v153
	v_mul_f32_e32 v154, v154, v173
	v_mul_f32_e32 v155, v155, v173
	v_mul_f32_e32 v156, v156, v173
	v_mul_f32_e32 v157, v157, v173
	v_mul_f32_e32 v158, v158, v173
	v_mul_f32_e32 v159, v159, v173
	v_mul_f32_e32 v160, v160, v173
	v_mul_f32_e32 v161, v161, v173
	v_mul_f32_e32 v162, v162, v173
	v_mul_f32_e32 v163, v163, v173
	v_mul_f32_e32 v164, v164, v173
	v_mul_f32_e32 v165, v165, v173
	v_mul_f32_e32 v166, v166, v173
	v_mul_f32_e32 v167, v167, v173
	v_mul_f32_e32 v168, v168, v173
	v_mul_f32_e32 v169, v169, v173
	v_mul_f32_e32 v154, v26, v154
	v_mul_f32_e32 v155, v27, v155
	v_mul_f32_e32 v156, v28, v156
	v_mul_f32_e32 v157, v29, v157
	v_mul_f32_e32 v158, v30, v158
	v_mul_f32_e32 v159, v31, v159
	v_mul_f32_e32 v160, v32, v160
	v_mul_f32_e32 v161, v33, v161
	v_mul_f32_e32 v162, v34, v162
	v_mul_f32_e32 v163, v35, v163
	v_mul_f32_e32 v164, v36, v164
	v_mul_f32_e32 v165, v37, v165
	v_mul_f32_e32 v166, v38, v166
	v_mul_f32_e32 v167, v39, v167
	v_mul_f32_e32 v168, v40, v168
	v_mul_f32_e32 v169, v41, v169
	s_add_u32 s10, s3, 16
	s_lshl_b32 s11, s10, 12
	s_add_u32 s8, s68, s11
	s_addc_u32 s9, s69, 0
	global_store_dwordx4 v170, v[138:141], s[8:9] offset:0
	global_store_dwordx4 v170, v[142:145], s[8:9] offset:1024
	global_store_dwordx4 v170, v[146:149], s[8:9] offset:2048
	global_store_dwordx4 v170, v[150:153], s[8:9] offset:3072
	s_add_u32 s8, s8, 0x1000
	s_addc_u32 s9, s9, 0
	global_store_dwordx4 v170, v[154:157], s[8:9] offset:0
	global_store_dwordx4 v170, v[158:161], s[8:9] offset:1024
	global_store_dwordx4 v170, v[162:165], s[8:9] offset:2048
	global_store_dwordx4 v170, v[166:169], s[8:9] offset:3072
	s_add_u32 s10, s3, 48
	s_lshl_b32 s11, s10, 12
	s_add_u32 s4, s36, s11
	s_addc_u32 s5, s37, 0
	s_lshl_b32 s11, s10, 11
	s_add_u32 s11, s11, 0x5100000
	s_add_u32 s6, s70, s11
	s_addc_u32 s7, s71, 0
	global_load_dwordx4 v[90:93], v170, s[4:5] offset:0
	global_load_dwordx4 v[94:97], v170, s[4:5] offset:1024
	global_load_dwordx4 v[98:101], v170, s[4:5] offset:2048
	global_load_dwordx4 v[102:105], v170, s[4:5] offset:3072
	global_load_dwordx2 v[122:123], v171, s[6:7] offset:0
	global_load_dwordx2 v[124:125], v171, s[6:7] offset:512
	global_load_dwordx2 v[126:127], v171, s[6:7] offset:1024
	global_load_dwordx2 v[128:129], v171, s[6:7] offset:1536
	s_add_u32 s4, s4, 0x1000
	s_addc_u32 s5, s5, 0
	s_add_u32 s6, s6, 0x800
	s_addc_u32 s7, s7, 0
	global_load_dwordx4 v[106:109], v170, s[4:5] offset:0
	global_load_dwordx4 v[110:113], v170, s[4:5] offset:1024
	global_load_dwordx4 v[114:117], v170, s[4:5] offset:2048
	global_load_dwordx4 v[118:121], v170, s[4:5] offset:3072
	global_load_dwordx2 v[130:131], v171, s[6:7] offset:0
	global_load_dwordx2 v[132:133], v171, s[6:7] offset:512
	global_load_dwordx2 v[134:135], v171, s[6:7] offset:1024
	global_load_dwordx2 v[136:137], v171, s[6:7] offset:1536
	s_waitcnt vmcnt(24)
; __device__ __forceinline__ float bf_lo(unsigned u) { return __uint_as_float(u << 16); }
; __device__ __forceinline__ float bf_hi(unsigned u) { return __uint_as_float(u & 0xffff0000u); }
; __device__ void final_phase(const Params& p) {
;     ...
;                 const f32x4 x0 = *(const f32x4*)(xp + c * 256 + lane * 4), x1 = *(const f32x4*)(xp + 1024 + c * 256 + lane * 4);
;                 const u32x2 y0 = *(const u32x2*)(yp + c * 256 + lane * 4), y1 = *(const u32x2*)(yp + 1024 + c * 256 + lane * 4);
;                 h0[c] = x0 + gt[c] * (f32x4){bf_lo(y0[0]), bf_hi(y0[0]), bf_lo(y0[1]), bf_hi(y0[1])};
;                 h1[c] = x1 + gt[c] * (f32x4){bf_lo(y1[0]), bf_hi(y1[0]), bf_lo(y1[1]), bf_hi(y1[1])};
;                 s0 += h0[c][0] * h0[c][0] + h0[c][1] * h0[c][1] + h0[c][2] * h0[c][2] + h0[c][3] * h0[c][3];
;                 s1 += h1[c][0] * h1[c][0] + h1[c][1] * h1[c][1] + h1[c][2] * h1[c][2] + h1[c][3] * h1[c][3];
;             }
; #pragma unroll
;             for (int m = 32; m >= 1; m >>= 1) { s0 += __shfl_xor(s0, m); s1 += __shfl_xor(s1, m); }
;             const float rs0 = rsqrtf(s0 * (1.f / 1024.f) + EPS), rs1 = rsqrtf(s1 * (1.f / 1024.f) + EPS);
; #pragma unroll
;             for (int c = 0; c < 4; ++c) { *(f32x4*)(op + c * 256 + lane * 4) = h0[c] * rs0 * g[c]; *(f32x4*)(op + 1024 + c * 256 + lane * 4) = h1[c] * rs1 * g[c]; }
	v_lshlrev_b32_e32 v174, 16, v74
	v_fma_f32 v138, v10, v174, v42
	v_and_b32_e32 v174, 0xffff0000, v74
	v_fma_f32 v139, v11, v174, v43
	v_lshlrev_b32_e32 v174, 16, v75
	v_fma_f32 v140, v12, v174, v44
	v_and_b32_e32 v174, 0xffff0000, v75
	v_fma_f32 v141, v13, v174, v45
	v_lshlrev_b32_e32 v174, 16, v76
	v_fma_f32 v142, v14, v174, v46
	v_and_b32_e32 v174, 0xffff0000, v76
	v_fma_f32 v143, v15, v174, v47
	v_lshlrev_b32_e32 v174, 16, v77
	v_fma_f32 v144, v16, v174, v48
	v_and_b32_e32 v174, 0xffff0000, v77
	v_fma_f32 v145, v17, v174, v49
	v_lshlrev_b32_e32 v174, 16, v78
	v_fma_f32 v146, v18, v174, v50
	v_and_b32_e32 v174, 0xffff0000, v78
	v_fma_f32 v147, v19, v174, v51
	v_lshlrev_b32_e32 v174, 16, v79
	v_fma_f32 v148, v20, v174, v52
	v_and_b32_e32 v174, 0xffff0000, v79
	v_fma_f32 v149, v21, v174, v53
	v_lshlrev_b32_e32 v174, 16, v80
	v_fma_f32 v150, v22, v174, v54
	v_and_b32_e32 v174, 0xffff0000, v80
	v_fma_f32 v151, v23, v174, v55
	v_lshlrev_b32_e32 v174, 16, v81
	v_fma_f32 v152, v24, v174, v56
	v_and_b32_e32 v174, 0xffff0000, v81
	v_fma_f32 v153, v25, v174, v57
	v_mul_f32_e32 v172, v138, v138
	v_fmac_f32_e32 v172, v139, v139
	v_fmac_f32_e32 v172, v140, v140
	v_fmac_f32_e32 v172, v141, v141
	v_fmac_f32_e32 v172, v142, v142
	v_fmac_f32_e32 v172, v143, v143
	v_fmac_f32_e32 v172, v144, v144
	v_fmac_f32_e32 v172, v145, v145
	v_fmac_f32_e32 v172, v146, v146
	v_fmac_f32_e32 v172, v147, v147
	v_fmac_f32_e32 v172, v148, v148
	v_fmac_f32_e32 v172, v149, v149
	v_fmac_f32_e32 v172, v150, v150
	v_fmac_f32_e32 v172, v151, v151
	v_fmac_f32_e32 v172, v152, v152
	v_fmac_f32_e32 v172, v153, v153
	v_lshlrev_b32_e32 v174, 16, v82
	v_fma_f32 v154, v10, v174, v58
	v_and_b32_e32 v174, 0xffff0000, v82
	v_fma_f32 v155, v11, v174, v59
	v_lshlrev_b32_e32 v174, 16, v83
	v_fma_f32 v156, v12, v174, v60
	v_and_b32_e32 v174, 0xffff0000, v83
	v_fma_f32 v157, v13, v174, v61
	v_lshlrev_b32_e32 v174, 16, v84
	v_fma_f32 v158, v14, v174, v62
	v_and_b32_e32 v174, 0xffff0000, v84
	v_fma_f32 v159, v15, v174, v63
	v_lshlrev_b32_e32 v174, 16, v85
	v_fma_f32 v160, v16, v174, v64
	v_and_b32_e32 v174, 0xffff0000, v85
	v_fma_f32 v161, v17, v174, v65
	v_lshlrev_b32_e32 v174, 16, v86
	v_fma_f32 v162, v18, v174, v66
	v_and_b32_e32 v174, 0xffff0000, v86
	v_fma_f32 v163, v19, v174, v67
	v_lshlrev_b32_e32 v174, 16, v87
	v_fma_f32 v164, v20, v174, v68
	v_and_b32_e32 v174, 0xffff0000, v87
	v_fma_f32 v165, v21, v174, v69
	v_lshlrev_b32_e32 v174, 16, v88
	v_fma_f32 v166, v22, v174, v70
	v_and_b32_e32 v174, 0xffff0000, v88
	v_fma_f32 v167, v23, v174, v71
	v_lshlrev_b32_e32 v174, 16, v89
	v_fma_f32 v168, v24, v174, v72
	v_and_b32_e32 v174, 0xffff0000, v89
	v_fma_f32 v169, v25, v174, v73
	v_mul_f32_e32 v173, v154, v154
	v_fmac_f32_e32 v173, v155, v155
	v_fmac_f32_e32 v173, v156, v156
	v_fmac_f32_e32 v173, v157, v157
	v_fmac_f32_e32 v173, v158, v158
	v_fmac_f32_e32 v173, v159, v159
	v_fmac_f32_e32 v173, v160, v160
	v_fmac_f32_e32 v173, v161, v161
	v_fmac_f32_e32 v173, v162, v162
	v_fmac_f32_e32 v173, v163, v163
	v_fmac_f32_e32 v173, v164, v164
	v_fmac_f32_e32 v173, v165, v165
	v_fmac_f32_e32 v173, v166, v166
	v_fmac_f32_e32 v173, v167, v167
	v_fmac_f32_e32 v173, v168, v168
	v_fmac_f32_e32 v173, v169, v169
	s_nop 1
	v_add_f32_dpp v172, v172, v172 row_shr:1 row_mask:0xf bank_mask:0xf bound_ctrl:1
	s_nop 1
	v_add_f32_dpp v173, v173, v173 row_shr:1 row_mask:0xf bank_mask:0xf bound_ctrl:1
	s_nop 0
	v_add_f32_dpp v172, v172, v172 row_shr:2 row_mask:0xf bank_mask:0xf bound_ctrl:1
	v_add_f32_dpp v173, v173, v173 row_shr:2 row_mask:0xf bank_mask:0xf bound_ctrl:1
	s_nop 0
	v_add_f32_dpp v172, v172, v172 row_shr:4 row_mask:0xf bank_mask:0xf bound_ctrl:1
	v_add_f32_dpp v173, v173, v173 row_shr:4 row_mask:0xf bank_mask:0xf bound_ctrl:1
	s_nop 0
	v_add_f32_dpp v172, v172, v172 row_shr:8 row_mask:0xf bank_mask:0xf bound_ctrl:1
	v_add_f32_dpp v173, v173, v173 row_shr:8 row_mask:0xf bank_mask:0xf bound_ctrl:1
	s_nop 0
	v_readlane_b32 s12, v172, 15
	v_readlane_b32 s13, v172, 31
	v_readlane_b32 s14, v172, 47
	v_readlane_b32 s15, v172, 63
	v_readlane_b32 s16, v173, 15
	v_readlane_b32 s17, v173, 31
	v_readlane_b32 s18, v173, 47
	v_readlane_b32 s19, v173, 63
	s_nop 1
	v_mov_b32_e32 v172, s12
	v_add_f32_e32 v172, s13, v172
	v_add_f32_e32 v172, s14, v172
	v_add_f32_e32 v172, s15, v172
	v_mov_b32_e32 v173, s16
	v_add_f32_e32 v173, s17, v173
	v_add_f32_e32 v173, s18, v173
	v_add_f32_e32 v173, s19, v173
	v_mov_b32_e32 v174, 0x358637bd
	v_fmac_f32_e32 v174, 0x3a800000, v172
	v_rsq_f32_e32 v172, v174
	v_mov_b32_e32 v174, 0x358637bd
	v_fmac_f32_e32 v174, 0x3a800000, v173
	v_rsq_f32_e32 v173, v174
	s_nop 0
	v_mul_f32_e32 v138, v138, v172
	v_mul_f32_e32 v139, v139, v172
	v_mul_f32_e32 v140, v140, v172
	v_mul_f32_e32 v141, v141, v172
	v_mul_f32_e32 v142, v142, v172
	v_mul_f32_e32 v143, v143, v172
	v_mul_f32_e32 v144, v144, v172
	v_mul_f32_e32 v145, v145, v172
	v_mul_f32_e32 v146, v146, v172
	v_mul_f32_e32 v147, v147, v172
	v_mul_f32_e32 v148, v148, v172
	v_mul_f32_e32 v149, v149, v172
	v_mul_f32_e32 v150, v150, v172
	v_mul_f32_e32 v151, v151, v172
	v_mul_f32_e32 v152, v152, v172
	v_mul_f32_e32 v153, v153, v172
	v_mul_f32_e32 v138, v26, v138
	v_mul_f32_e32 v139, v27, v139
	v_mul_f32_e32 v140, v28, v140
	v_mul_f32_e32 v141, v29, v141
	v_mul_f32_e32 v142, v30, v142
	v_mul_f32_e32 v143, v31, v143
	v_mul_f32_e32 v144, v32, v144
	v_mul_f32_e32 v145, v33, v145
	v_mul_f32_e32 v146, v34, v146
	v_mul_f32_e32 v147, v35, v147
	v_mul_f32_e32 v148, v36, v148
	v_mul_f32_e32 v149, v37, v149
	v_mul_f32_e32 v150, v38, v150
	v_mul_f32_e32 v151, v39, v151
	v_mul_f32_e32 v152, v40, v152
	v_mul_f32_e32 v153, v41, v153
	v_mul_f32_e32 v154, v154, v173
; __device__ __forceinline__ float bf_lo(unsigned u) { return __uint_as_float(u << 16); }
; __device__ __forceinline__ float bf_hi(unsigned u) { return __uint_as_float(u & 0xffff0000u); }
; __device__ void final_phase(const Params& p) {
;     ...
;                 const f32x4 x0 = *(const f32x4*)(xp + c * 256 + lane * 4), x1 = *(const f32x4*)(xp + 1024 + c * 256 + lane * 4);
;                 const u32x2 y0 = *(const u32x2*)(yp + c * 256 + lane * 4), y1 = *(const u32x2*)(yp + 1024 + c * 256 + lane * 4);
;                 h0[c] = x0 + gt[c] * (f32x4){bf_lo(y0[0]), bf_hi(y0[0]), bf_lo(y0[1]), bf_hi(y0[1])};
;                 h1[c] = x1 + gt[c] * (f32x4){bf_lo(y1[0]), bf_hi(y1[0]), bf_lo(y1[1]), bf_hi(y1[1])};
;                 s0 += h0[c][0] * h0[c][0] + h0[c][1] * h0[c][1] + h0[c][2] * h0[c][2] + h0[c][3] * h0[c][3];
;                 s1 += h1[c][0] * h1[c][0] + h1[c][1] * h1[c][1] + h1[c][2] * h1[c][2] + h1[c][3] * h1[c][3];
;             }
; #pragma unroll
;             for (int m = 32; m >= 1; m >>= 1) { s0 += __shfl_xor(s0, m); s1 += __shfl_xor(s1, m); }
;             const float rs0 = rsqrtf(s0 * (1.f / 1024.f) + EPS), rs1 = rsqrtf(s1 * (1.f / 1024.f) + EPS);
; #pragma unroll
;             for (int c = 0; c < 4; ++c) { *(f32x4*)(op + c * 256 + lane * 4) = h0[c] * rs0 * g[c]; *(f32x4*)(op + 1024 + c * 256 + lane * 4) = h1[c] * rs1 * g[c]; }
	v_mul_f32_e32 v155, v155, v173
	v_mul_f32_e32 v156, v156, v173
	v_mul_f32_e32 v157, v157, v173
	v_mul_f32_e32 v158, v158, v173
	v_mul_f32_e32 v159, v159, v173
	v_mul_f32_e32 v160, v160, v173
	v_mul_f32_e32 v161, v161, v173
	v_mul_f32_e32 v162, v162, v173
	v_mul_f32_e32 v163, v163, v173
	v_mul_f32_e32 v164, v164, v173
	v_mul_f32_e32 v165, v165, v173
	v_mul_f32_e32 v166, v166, v173
	v_mul_f32_e32 v167, v167, v173
	v_mul_f32_e32 v168, v168, v173
	v_mul_f32_e32 v169, v169, v173
	v_mul_f32_e32 v154, v26, v154
	v_mul_f32_e32 v155, v27, v155
	v_mul_f32_e32 v156, v28, v156
	v_mul_f32_e32 v157, v29, v157
	v_mul_f32_e32 v158, v30, v158
	v_mul_f32_e32 v159, v31, v159
	v_mul_f32_e32 v160, v32, v160
	v_mul_f32_e32 v161, v33, v161
	v_mul_f32_e32 v162, v34, v162
	v_mul_f32_e32 v163, v35, v163
	v_mul_f32_e32 v164, v36, v164
	v_mul_f32_e32 v165, v37, v165
	v_mul_f32_e32 v166, v38, v166
	v_mul_f32_e32 v167, v39, v167
	v_mul_f32_e32 v168, v40, v168
	v_mul_f32_e32 v169, v41, v169
	s_add_u32 s10, s3, 32
	s_lshl_b32 s11, s10, 12
	s_add_u32 s8, s68, s11
	s_addc_u32 s9, s69, 0
	global_store_dwordx4 v170, v[138:141], s[8:9] offset:0
	global_store_dwordx4 v170, v[142:145], s[8:9] offset:1024
	global_store_dwordx4 v170, v[146:149], s[8:9] offset:2048
	global_store_dwordx4 v170, v[150:153], s[8:9] offset:3072
	s_add_u32 s8, s8, 0x1000
	s_addc_u32 s9, s9, 0
	global_store_dwordx4 v170, v[154:157], s[8:9] offset:0
	global_store_dwordx4 v170, v[158:161], s[8:9] offset:1024
	global_store_dwordx4 v170, v[162:165], s[8:9] offset:2048
	global_store_dwordx4 v170, v[166:169], s[8:9] offset:3072
	s_add_u32 s10, s3, 64
	s_lshl_b32 s11, s10, 12
	s_add_u32 s4, s36, s11
	s_addc_u32 s5, s37, 0
	s_lshl_b32 s11, s10, 11
	s_add_u32 s11, s11, 0x5100000
	s_add_u32 s6, s70, s11
	s_addc_u32 s7, s71, 0
	global_load_dwordx4 v[42:45], v170, s[4:5] offset:0
	global_load_dwordx4 v[46:49], v170, s[4:5] offset:1024
	global_load_dwordx4 v[50:53], v170, s[4:5] offset:2048
	global_load_dwordx4 v[54:57], v170, s[4:5] offset:3072
	global_load_dwordx2 v[74:75], v171, s[6:7] offset:0
	global_load_dwordx2 v[76:77], v171, s[6:7] offset:512
	global_load_dwordx2 v[78:79], v171, s[6:7] offset:1024
	global_load_dwordx2 v[80:81], v171, s[6:7] offset:1536
	s_add_u32 s4, s4, 0x1000
	s_addc_u32 s5, s5, 0
	s_add_u32 s6, s6, 0x800
	s_addc_u32 s7, s7, 0
	global_load_dwordx4 v[58:61], v170, s[4:5] offset:0
	global_load_dwordx4 v[62:65], v170, s[4:5] offset:1024
	global_load_dwordx4 v[66:69], v170, s[4:5] offset:2048
	global_load_dwordx4 v[70:73], v170, s[4:5] offset:3072
	global_load_dwordx2 v[82:83], v171, s[6:7] offset:0
	global_load_dwordx2 v[84:85], v171, s[6:7] offset:512
	global_load_dwordx2 v[86:87], v171, s[6:7] offset:1024
	global_load_dwordx2 v[88:89], v171, s[6:7] offset:1536
	s_waitcnt vmcnt(24)
	v_lshlrev_b32_e32 v174, 16, v122
	v_fma_f32 v138, v10, v174, v90
	v_and_b32_e32 v174, 0xffff0000, v122
	v_fma_f32 v139, v11, v174, v91
	v_lshlrev_b32_e32 v174, 16, v123
	v_fma_f32 v140, v12, v174, v92
	v_and_b32_e32 v174, 0xffff0000, v123
	v_fma_f32 v141, v13, v174, v93
	v_lshlrev_b32_e32 v174, 16, v124
	v_fma_f32 v142, v14, v174, v94
	v_and_b32_e32 v174, 0xffff0000, v124
	v_fma_f32 v143, v15, v174, v95
	v_lshlrev_b32_e32 v174, 16, v125
	v_fma_f32 v144, v16, v174, v96
	v_and_b32_e32 v174, 0xffff0000, v125
	v_fma_f32 v145, v17, v174, v97
	v_lshlrev_b32_e32 v174, 16, v126
	v_fma_f32 v146, v18, v174, v98
	v_and_b32_e32 v174, 0xffff0000, v126
	v_fma_f32 v147, v19, v174, v99
	v_lshlrev_b32_e32 v174, 16, v127
	v_fma_f32 v148, v20, v174, v100
	v_and_b32_e32 v174, 0xffff0000, v127
	v_fma_f32 v149, v21, v174, v101
	v_lshlrev_b32_e32 v174, 16, v128
	v_fma_f32 v150, v22, v174, v102
	v_and_b32_e32 v174, 0xffff0000, v128
	v_fma_f32 v151, v23, v174, v103
	v_lshlrev_b32_e32 v174, 16, v129
	v_fma_f32 v152, v24, v174, v104
	v_and_b32_e32 v174, 0xffff0000, v129
	v_fma_f32 v153, v25, v174, v105
	v_mul_f32_e32 v172, v138, v138
	v_fmac_f32_e32 v172, v139, v139
	v_fmac_f32_e32 v172, v140, v140
	v_fmac_f32_e32 v172, v141, v141
	v_fmac_f32_e32 v172, v142, v142
	v_fmac_f32_e32 v172, v143, v143
	v_fmac_f32_e32 v172, v144, v144
	v_fmac_f32_e32 v172, v145, v145
	v_fmac_f32_e32 v172, v146, v146
	v_fmac_f32_e32 v172, v147, v147
	v_fmac_f32_e32 v172, v148, v148
	v_fmac_f32_e32 v172, v149, v149
	v_fmac_f32_e32 v172, v150, v150
	v_fmac_f32_e32 v172, v151, v151
	v_fmac_f32_e32 v172, v152, v152
	v_fmac_f32_e32 v172, v153, v153
	v_lshlrev_b32_e32 v174, 16, v130
	v_fma_f32 v154, v10, v174, v106
	v_and_b32_e32 v174, 0xffff0000, v130
	v_fma_f32 v155, v11, v174, v107
	v_lshlrev_b32_e32 v174, 16, v131
	v_fma_f32 v156, v12, v174, v108
	v_and_b32_e32 v174, 0xffff0000, v131
	v_fma_f32 v157, v13, v174, v109
	v_lshlrev_b32_e32 v174, 16, v132
	v_fma_f32 v158, v14, v174, v110
	v_and_b32_e32 v174, 0xffff0000, v132
	v_fma_f32 v159, v15, v174, v111
	v_lshlrev_b32_e32 v174, 16, v133
	v_fma_f32 v160, v16, v174, v112
	v_and_b32_e32 v174, 0xffff0000, v133
	v_fma_f32 v161, v17, v174, v113
	v_lshlrev_b32_e32 v174, 16, v134
	v_fma_f32 v162, v18, v174, v114
	v_and_b32_e32 v174, 0xffff0000, v134
	v_fma_f32 v163, v19, v174, v115
	v_lshlrev_b32_e32 v174, 16, v135
	v_fma_f32 v164, v20, v174, v116
	v_and_b32_e32 v174, 0xffff0000, v135
	v_fma_f32 v165, v21, v174, v117
	v_lshlrev_b32_e32 v174, 16, v136
	v_fma_f32 v166, v22, v174, v118
	v_and_b32_e32 v174, 0xffff0000, v136
	v_fma_f32 v167, v23, v174, v119
	v_lshlrev_b32_e32 v174, 16, v137
	v_fma_f32 v168, v24, v174, v120
	v_and_b32_e32 v174, 0xffff0000, v137
	v_fma_f32 v169, v25, v174, v121
	v_mul_f32_e32 v173, v154, v154
	v_fmac_f32_e32 v173, v155, v155
	v_fmac_f32_e32 v173, v156, v156
	v_fmac_f32_e32 v173, v157, v157
; __device__ void final_phase(const Params& p) {
;     ...
;                 s0 += h0[c][0] * h0[c][0] + h0[c][1] * h0[c][1] + h0[c][2] * h0[c][2] + h0[c][3] * h0[c][3];
;                 s1 += h1[c][0] * h1[c][0] + h1[c][1] * h1[c][1] + h1[c][2] * h1[c][2] + h1[c][3] * h1[c][3];
;             }
; #pragma unroll
;             for (int m = 32; m >= 1; m >>= 1) { s0 += __shfl_xor(s0, m); s1 += __shfl_xor(s1, m); }
;             const float rs0 = rsqrtf(s0 * (1.f / 1024.f) + EPS), rs1 = rsqrtf(s1 * (1.f / 1024.f) + EPS);
; #pragma unroll
;             for (int c = 0; c < 4; ++c) { *(f32x4*)(op + c * 256 + lane * 4) = h0[c] * rs0 * g[c]; *(f32x4*)(op + 1024 + c * 256 + lane * 4) = h1[c] * rs1 * g[c]; }
	v_fmac_f32_e32 v173, v158, v158
	v_fmac_f32_e32 v173, v159, v159
	v_fmac_f32_e32 v173, v160, v160
	v_fmac_f32_e32 v173, v161, v161
	v_fmac_f32_e32 v173, v162, v162
	v_fmac_f32_e32 v173, v163, v163
	v_fmac_f32_e32 v173, v164, v164
	v_fmac_f32_e32 v173, v165, v165
	v_fmac_f32_e32 v173, v166, v166
	v_fmac_f32_e32 v173, v167, v167
	v_fmac_f32_e32 v173, v168, v168
	v_fmac_f32_e32 v173, v169, v169
	s_nop 1
	v_add_f32_dpp v172, v172, v172 row_shr:1 row_mask:0xf bank_mask:0xf bound_ctrl:1
	s_nop 1
	v_add_f32_dpp v173, v173, v173 row_shr:1 row_mask:0xf bank_mask:0xf bound_ctrl:1
	s_nop 0
	v_add_f32_dpp v172, v172, v172 row_shr:2 row_mask:0xf bank_mask:0xf bound_ctrl:1
	v_add_f32_dpp v173, v173, v173 row_shr:2 row_mask:0xf bank_mask:0xf bound_ctrl:1
	s_nop 0
	v_add_f32_dpp v172, v172, v172 row_shr:4 row_mask:0xf bank_mask:0xf bound_ctrl:1
	v_add_f32_dpp v173, v173, v173 row_shr:4 row_mask:0xf bank_mask:0xf bound_ctrl:1
	s_nop 0
	v_add_f32_dpp v172, v172, v172 row_shr:8 row_mask:0xf bank_mask:0xf bound_ctrl:1
	v_add_f32_dpp v173, v173, v173 row_shr:8 row_mask:0xf bank_mask:0xf bound_ctrl:1
	s_nop 0
	v_readlane_b32 s12, v172, 15
	v_readlane_b32 s13, v172, 31
	v_readlane_b32 s14, v172, 47
	v_readlane_b32 s15, v172, 63
	v_readlane_b32 s16, v173, 15
	v_readlane_b32 s17, v173, 31
	v_readlane_b32 s18, v173, 47
	v_readlane_b32 s19, v173, 63
	s_nop 1
	v_mov_b32_e32 v172, s12
	v_add_f32_e32 v172, s13, v172
	v_add_f32_e32 v172, s14, v172
	v_add_f32_e32 v172, s15, v172
	v_mov_b32_e32 v173, s16
	v_add_f32_e32 v173, s17, v173
	v_add_f32_e32 v173, s18, v173
	v_add_f32_e32 v173, s19, v173
	v_mov_b32_e32 v174, 0x358637bd
	v_fmac_f32_e32 v174, 0x3a800000, v172
	v_rsq_f32_e32 v172, v174
	v_mov_b32_e32 v174, 0x358637bd
	v_fmac_f32_e32 v174, 0x3a800000, v173
	v_rsq_f32_e32 v173, v174
	s_nop 0
	v_mul_f32_e32 v138, v138, v172
	v_mul_f32_e32 v139, v139, v172
	v_mul_f32_e32 v140, v140, v172
	v_mul_f32_e32 v141, v141, v172
	v_mul_f32_e32 v142, v142, v172
	v_mul_f32_e32 v143, v143, v172
	v_mul_f32_e32 v144, v144, v172
	v_mul_f32_e32 v145, v145, v172
	v_mul_f32_e32 v146, v146, v172
	v_mul_f32_e32 v147, v147, v172
	v_mul_f32_e32 v148, v148, v172
	v_mul_f32_e32 v149, v149, v172
	v_mul_f32_e32 v150, v150, v172
	v_mul_f32_e32 v151, v151, v172
	v_mul_f32_e32 v152, v152, v172
	v_mul_f32_e32 v153, v153, v172
	v_mul_f32_e32 v138, v26, v138
	v_mul_f32_e32 v139, v27, v139
	v_mul_f32_e32 v140, v28, v140
	v_mul_f32_e32 v141, v29, v141
	v_mul_f32_e32 v142, v30, v142
	v_mul_f32_e32 v143, v31, v143
	v_mul_f32_e32 v144, v32, v144
	v_mul_f32_e32 v145, v33, v145
	v_mul_f32_e32 v146, v34, v146
	v_mul_f32_e32 v147, v35, v147
	v_mul_f32_e32 v148, v36, v148
	v_mul_f32_e32 v149, v37, v149
	v_mul_f32_e32 v150, v38, v150
	v_mul_f32_e32 v151, v39, v151
	v_mul_f32_e32 v152, v40, v152
	v_mul_f32_e32 v153, v41, v153
	v_mul_f32_e32 v154, v154, v173
	v_mul_f32_e32 v155, v155, v173
	v_mul_f32_e32 v156, v156, v173
	v_mul_f32_e32 v157, v157, v173
	v_mul_f32_e32 v158, v158, v173
	v_mul_f32_e32 v159, v159, v173
	v_mul_f32_e32 v160, v160, v173
	v_mul_f32_e32 v161, v161, v173
	v_mul_f32_e32 v162, v162, v173
	v_mul_f32_e32 v163, v163, v173
	v_mul_f32_e32 v164, v164, v173
	v_mul_f32_e32 v165, v165, v173
	v_mul_f32_e32 v166, v166, v173
	v_mul_f32_e32 v167, v167, v173
	v_mul_f32_e32 v168, v168, v173
	v_mul_f32_e32 v169, v169, v173
	v_mul_f32_e32 v154, v26, v154
	v_mul_f32_e32 v155, v27, v155
	v_mul_f32_e32 v156, v28, v156
	v_mul_f32_e32 v157, v29, v157
	v_mul_f32_e32 v158, v30, v158
	v_mul_f32_e32 v159, v31, v159
	v_mul_f32_e32 v160, v32, v160
	v_mul_f32_e32 v161, v33, v161
	v_mul_f32_e32 v162, v34, v162
	v_mul_f32_e32 v163, v35, v163
	v_mul_f32_e32 v164, v36, v164
	v_mul_f32_e32 v165, v37, v165
	v_mul_f32_e32 v166, v38, v166
	v_mul_f32_e32 v167, v39, v167
	v_mul_f32_e32 v168, v40, v168
	v_mul_f32_e32 v169, v41, v169
	s_add_u32 s10, s3, 48
	s_lshl_b32 s11, s10, 12
	s_add_u32 s8, s68, s11
	s_addc_u32 s9, s69, 0
	global_store_dwordx4 v170, v[138:141], s[8:9] offset:0
	global_store_dwordx4 v170, v[142:145], s[8:9] offset:1024
	global_store_dwordx4 v170, v[146:149], s[8:9] offset:2048
	global_store_dwordx4 v170, v[150:153], s[8:9] offset:3072
	s_add_u32 s8, s8, 0x1000
	s_addc_u32 s9, s9, 0
	global_store_dwordx4 v170, v[154:157], s[8:9] offset:0
	global_store_dwordx4 v170, v[158:161], s[8:9] offset:1024
	global_store_dwordx4 v170, v[162:165], s[8:9] offset:2048
	global_store_dwordx4 v170, v[166:169], s[8:9] offset:3072
	s_add_u32 s10, s3, 80
	s_lshl_b32 s11, s10, 12
	s_add_u32 s4, s36, s11
	s_addc_u32 s5, s37, 0
	s_lshl_b32 s11, s10, 11
	s_add_u32 s11, s11, 0x5100000
	s_add_u32 s6, s70, s11
	s_addc_u32 s7, s71, 0
	global_load_dwordx4 v[90:93], v170, s[4:5] offset:0
	global_load_dwordx4 v[94:97], v170, s[4:5] offset:1024
	global_load_dwordx4 v[98:101], v170, s[4:5] offset:2048
	global_load_dwordx4 v[102:105], v170, s[4:5] offset:3072
	global_load_dwordx2 v[122:123], v171, s[6:7] offset:0
	global_load_dwordx2 v[124:125], v171, s[6:7] offset:512
	global_load_dwordx2 v[126:127], v171, s[6:7] offset:1024
	global_load_dwordx2 v[128:129], v171, s[6:7] offset:1536
	s_add_u32 s4, s4, 0x1000
	s_addc_u32 s5, s5, 0
	s_add_u32 s6, s6, 0x800
	s_addc_u32 s7, s7, 0
	global_load_dwordx4 v[106:109], v170, s[4:5] offset:0
	global_load_dwordx4 v[110:113], v170, s[4:5] offset:1024
	global_load_dwordx4 v[114:117], v170, s[4:5] offset:2048
	global_load_dwordx4 v[118:121], v170, s[4:5] offset:3072
	global_load_dwordx2 v[130:131], v171, s[6:7] offset:0
	global_load_dwordx2 v[132:133], v171, s[6:7] offset:512
	global_load_dwordx2 v[134:135], v171, s[6:7] offset:1024
	global_load_dwordx2 v[136:137], v171, s[6:7] offset:1536
	s_waitcnt vmcnt(24)
; __device__ __forceinline__ float bf_lo(unsigned u) { return __uint_as_float(u << 16); }
; __device__ __forceinline__ float bf_hi(unsigned u) { return __uint_as_float(u & 0xffff0000u); }
; __device__ void final_phase(const Params& p) {
;     ...
;                 const f32x4 x0 = *(const f32x4*)(xp + c * 256 + lane * 4), x1 = *(const f32x4*)(xp + 1024 + c * 256 + lane * 4);
;                 const u32x2 y0 = *(const u32x2*)(yp + c * 256 + lane * 4), y1 = *(const u32x2*)(yp + 1024 + c * 256 + lane * 4);
;                 h0[c] = x0 + gt[c] * (f32x4){bf_lo(y0[0]), bf_hi(y0[0]), bf_lo(y0[1]), bf_hi(y0[1])};
;                 h1[c] = x1 + gt[c] * (f32x4){bf_lo(y1[0]), bf_hi(y1[0]), bf_lo(y1[1]), bf_hi(y1[1])};
;                 s0 += h0[c][0] * h0[c][0] + h0[c][1] * h0[c][1] + h0[c][2] * h0[c][2] + h0[c][3] * h0[c][3];
;                 s1 += h1[c][0] * h1[c][0] + h1[c][1] * h1[c][1] + h1[c][2] * h1[c][2] + h1[c][3] * h1[c][3];
;             }
; #pragma unroll
;             for (int m = 32; m >= 1; m >>= 1) { s0 += __shfl_xor(s0, m); s1 += __shfl_xor(s1, m); }
;             const float rs0 = rsqrtf(s0 * (1.f / 1024.f) + EPS), rs1 = rsqrtf(s1 * (1.f / 1024.f) + EPS);
; #pragma unroll
;             for (int c = 0; c < 4; ++c) { *(f32x4*)(op + c * 256 + lane * 4) = h0[c] * rs0 * g[c]; *(f32x4*)(op + 1024 + c * 256 + lane * 4) = h1[c] * rs1 * g[c]; }
	v_lshlrev_b32_e32 v174, 16, v74
	v_fma_f32 v138, v10, v174, v42
	v_and_b32_e32 v174, 0xffff0000, v74
	v_fma_f32 v139, v11, v174, v43
	v_lshlrev_b32_e32 v174, 16, v75
	v_fma_f32 v140, v12, v174, v44
	v_and_b32_e32 v174, 0xffff0000, v75
	v_fma_f32 v141, v13, v174, v45
	v_lshlrev_b32_e32 v174, 16, v76
	v_fma_f32 v142, v14, v174, v46
	v_and_b32_e32 v174, 0xffff0000, v76
	v_fma_f32 v143, v15, v174, v47
	v_lshlrev_b32_e32 v174, 16, v77
	v_fma_f32 v144, v16, v174, v48
	v_and_b32_e32 v174, 0xffff0000, v77
	v_fma_f32 v145, v17, v174, v49
	v_lshlrev_b32_e32 v174, 16, v78
	v_fma_f32 v146, v18, v174, v50
	v_and_b32_e32 v174, 0xffff0000, v78
	v_fma_f32 v147, v19, v174, v51
	v_lshlrev_b32_e32 v174, 16, v79
	v_fma_f32 v148, v20, v174, v52
	v_and_b32_e32 v174, 0xffff0000, v79
	v_fma_f32 v149, v21, v174, v53
	v_lshlrev_b32_e32 v174, 16, v80
	v_fma_f32 v150, v22, v174, v54
	v_and_b32_e32 v174, 0xffff0000, v80
	v_fma_f32 v151, v23, v174, v55
	v_lshlrev_b32_e32 v174, 16, v81
	v_fma_f32 v152, v24, v174, v56
	v_and_b32_e32 v174, 0xffff0000, v81
	v_fma_f32 v153, v25, v174, v57
	v_mul_f32_e32 v172, v138, v138
	v_fmac_f32_e32 v172, v139, v139
	v_fmac_f32_e32 v172, v140, v140
	v_fmac_f32_e32 v172, v141, v141
	v_fmac_f32_e32 v172, v142, v142
	v_fmac_f32_e32 v172, v143, v143
	v_fmac_f32_e32 v172, v144, v144
	v_fmac_f32_e32 v172, v145, v145
	v_fmac_f32_e32 v172, v146, v146
	v_fmac_f32_e32 v172, v147, v147
	v_fmac_f32_e32 v172, v148, v148
	v_fmac_f32_e32 v172, v149, v149
	v_fmac_f32_e32 v172, v150, v150
	v_fmac_f32_e32 v172, v151, v151
	v_fmac_f32_e32 v172, v152, v152
	v_fmac_f32_e32 v172, v153, v153
	v_lshlrev_b32_e32 v174, 16, v82
	v_fma_f32 v154, v10, v174, v58
	v_and_b32_e32 v174, 0xffff0000, v82
	v_fma_f32 v155, v11, v174, v59
	v_lshlrev_b32_e32 v174, 16, v83
	v_fma_f32 v156, v12, v174, v60
	v_and_b32_e32 v174, 0xffff0000, v83
	v_fma_f32 v157, v13, v174, v61
	v_lshlrev_b32_e32 v174, 16, v84
	v_fma_f32 v158, v14, v174, v62
	v_and_b32_e32 v174, 0xffff0000, v84
	v_fma_f32 v159, v15, v174, v63
	v_lshlrev_b32_e32 v174, 16, v85
	v_fma_f32 v160, v16, v174, v64
	v_and_b32_e32 v174, 0xffff0000, v85
	v_fma_f32 v161, v17, v174, v65
	v_lshlrev_b32_e32 v174, 16, v86
	v_fma_f32 v162, v18, v174, v66
	v_and_b32_e32 v174, 0xffff0000, v86
	v_fma_f32 v163, v19, v174, v67
	v_lshlrev_b32_e32 v174, 16, v87
	v_fma_f32 v164, v20, v174, v68
	v_and_b32_e32 v174, 0xffff0000, v87
	v_fma_f32 v165, v21, v174, v69
	v_lshlrev_b32_e32 v174, 16, v88
	v_fma_f32 v166, v22, v174, v70
	v_and_b32_e32 v174, 0xffff0000, v88
	v_fma_f32 v167, v23, v174, v71
	v_lshlrev_b32_e32 v174, 16, v89
	v_fma_f32 v168, v24, v174, v72
	v_and_b32_e32 v174, 0xffff0000, v89
	v_fma_f32 v169, v25, v174, v73
	v_mul_f32_e32 v173, v154, v154
	v_fmac_f32_e32 v173, v155, v155
	v_fmac_f32_e32 v173, v156, v156
	v_fmac_f32_e32 v173, v157, v157
	v_fmac_f32_e32 v173, v158, v158
	v_fmac_f32_e32 v173, v159, v159
	v_fmac_f32_e32 v173, v160, v160
	v_fmac_f32_e32 v173, v161, v161
	v_fmac_f32_e32 v173, v162, v162
	v_fmac_f32_e32 v173, v163, v163
	v_fmac_f32_e32 v173, v164, v164
	v_fmac_f32_e32 v173, v165, v165
	v_fmac_f32_e32 v173, v166, v166
	v_fmac_f32_e32 v173, v167, v167
	v_fmac_f32_e32 v173, v168, v168
	v_fmac_f32_e32 v173, v169, v169
	s_nop 1
	v_add_f32_dpp v172, v172, v172 row_shr:1 row_mask:0xf bank_mask:0xf bound_ctrl:1
	s_nop 1
	v_add_f32_dpp v173, v173, v173 row_shr:1 row_mask:0xf bank_mask:0xf bound_ctrl:1
	s_nop 0
	v_add_f32_dpp v172, v172, v172 row_shr:2 row_mask:0xf bank_mask:0xf bound_ctrl:1
	v_add_f32_dpp v173, v173, v173 row_shr:2 row_mask:0xf bank_mask:0xf bound_ctrl:1
	s_nop 0
	v_add_f32_dpp v172, v172, v172 row_shr:4 row_mask:0xf bank_mask:0xf bound_ctrl:1
	v_add_f32_dpp v173, v173, v173 row_shr:4 row_mask:0xf bank_mask:0xf bound_ctrl:1
	s_nop 0
	v_add_f32_dpp v172, v172, v172 row_shr:8 row_mask:0xf bank_mask:0xf bound_ctrl:1
	v_add_f32_dpp v173, v173, v173 row_shr:8 row_mask:0xf bank_mask:0xf bound_ctrl:1
	s_nop 0
	v_readlane_b32 s12, v172, 15
	v_readlane_b32 s13, v172, 31
	v_readlane_b32 s14, v172, 47
	v_readlane_b32 s15, v172, 63
	v_readlane_b32 s16, v173, 15
	v_readlane_b32 s17, v173, 31
	v_readlane_b32 s18, v173, 47
	v_readlane_b32 s19, v173, 63
	s_nop 1
	v_mov_b32_e32 v172, s12
	v_add_f32_e32 v172, s13, v172
	v_add_f32_e32 v172, s14, v172
	v_add_f32_e32 v172, s15, v172
	v_mov_b32_e32 v173, s16
	v_add_f32_e32 v173, s17, v173
	v_add_f32_e32 v173, s18, v173
	v_add_f32_e32 v173, s19, v173
	v_mov_b32_e32 v174, 0x358637bd
	v_fmac_f32_e32 v174, 0x3a800000, v172
	v_rsq_f32_e32 v172, v174
	v_mov_b32_e32 v174, 0x358637bd
	v_fmac_f32_e32 v174, 0x3a800000, v173
	v_rsq_f32_e32 v173, v174
	s_nop 0
	v_mul_f32_e32 v138, v138, v172
	v_mul_f32_e32 v139, v139, v172
	v_mul_f32_e32 v140, v140, v172
	v_mul_f32_e32 v141, v141, v172
	v_mul_f32_e32 v142, v142, v172
	v_mul_f32_e32 v143, v143, v172
	v_mul_f32_e32 v144, v144, v172
	v_mul_f32_e32 v145, v145, v172
	v_mul_f32_e32 v146, v146, v172
	v_mul_f32_e32 v147, v147, v172
	v_mul_f32_e32 v148, v148, v172
	v_mul_f32_e32 v149, v149, v172
	v_mul_f32_e32 v150, v150, v172
	v_mul_f32_e32 v151, v151, v172
	v_mul_f32_e32 v152, v152, v172
	v_mul_f32_e32 v153, v153, v172
	v_mul_f32_e32 v138, v26, v138
	v_mul_f32_e32 v139, v27, v139
	v_mul_f32_e32 v140, v28, v140
	v_mul_f32_e32 v141, v29, v141
	v_mul_f32_e32 v142, v30, v142
	v_mul_f32_e32 v143, v31, v143
	v_mul_f32_e32 v144, v32, v144
	v_mul_f32_e32 v145, v33, v145
	v_mul_f32_e32 v146, v34, v146
	v_mul_f32_e32 v147, v35, v147
	v_mul_f32_e32 v148, v36, v148
	v_mul_f32_e32 v149, v37, v149
	v_mul_f32_e32 v150, v38, v150
	v_mul_f32_e32 v151, v39, v151
	v_mul_f32_e32 v152, v40, v152
	v_mul_f32_e32 v153, v41, v153
	v_mul_f32_e32 v154, v154, v173
; __device__ __forceinline__ float bf_lo(unsigned u) { return __uint_as_float(u << 16); }
; __device__ __forceinline__ float bf_hi(unsigned u) { return __uint_as_float(u & 0xffff0000u); }
; __device__ void final_phase(const Params& p) {
;     ...
;                 const f32x4 x0 = *(const f32x4*)(xp + c * 256 + lane * 4), x1 = *(const f32x4*)(xp + 1024 + c * 256 + lane * 4);
;                 const u32x2 y0 = *(const u32x2*)(yp + c * 256 + lane * 4), y1 = *(const u32x2*)(yp + 1024 + c * 256 + lane * 4);
;                 h0[c] = x0 + gt[c] * (f32x4){bf_lo(y0[0]), bf_hi(y0[0]), bf_lo(y0[1]), bf_hi(y0[1])};
;                 h1[c] = x1 + gt[c] * (f32x4){bf_lo(y1[0]), bf_hi(y1[0]), bf_lo(y1[1]), bf_hi(y1[1])};
;                 s0 += h0[c][0] * h0[c][0] + h0[c][1] * h0[c][1] + h0[c][2] * h0[c][2] + h0[c][3] * h0[c][3];
;                 s1 += h1[c][0] * h1[c][0] + h1[c][1] * h1[c][1] + h1[c][2] * h1[c][2] + h1[c][3] * h1[c][3];
;             }
; #pragma unroll
;             for (int m = 32; m >= 1; m >>= 1) { s0 += __shfl_xor(s0, m); s1 += __shfl_xor(s1, m); }
;             const float rs0 = rsqrtf(s0 * (1.f / 1024.f) + EPS), rs1 = rsqrtf(s1 * (1.f / 1024.f) + EPS);
; #pragma unroll
;             for (int c = 0; c < 4; ++c) { *(f32x4*)(op + c * 256 + lane * 4) = h0[c] * rs0 * g[c]; *(f32x4*)(op + 1024 + c * 256 + lane * 4) = h1[c] * rs1 * g[c]; }
	v_mul_f32_e32 v155, v155, v173
	v_mul_f32_e32 v156, v156, v173
	v_mul_f32_e32 v157, v157, v173
	v_mul_f32_e32 v158, v158, v173
	v_mul_f32_e32 v159, v159, v173
	v_mul_f32_e32 v160, v160, v173
	v_mul_f32_e32 v161, v161, v173
	v_mul_f32_e32 v162, v162, v173
	v_mul_f32_e32 v163, v163, v173
	v_mul_f32_e32 v164, v164, v173
	v_mul_f32_e32 v165, v165, v173
	v_mul_f32_e32 v166, v166, v173
	v_mul_f32_e32 v167, v167, v173
	v_mul_f32_e32 v168, v168, v173
	v_mul_f32_e32 v169, v169, v173
	v_mul_f32_e32 v154, v26, v154
	v_mul_f32_e32 v155, v27, v155
	v_mul_f32_e32 v156, v28, v156
	v_mul_f32_e32 v157, v29, v157
	v_mul_f32_e32 v158, v30, v158
	v_mul_f32_e32 v159, v31, v159
	v_mul_f32_e32 v160, v32, v160
	v_mul_f32_e32 v161, v33, v161
	v_mul_f32_e32 v162, v34, v162
	v_mul_f32_e32 v163, v35, v163
	v_mul_f32_e32 v164, v36, v164
	v_mul_f32_e32 v165, v37, v165
	v_mul_f32_e32 v166, v38, v166
	v_mul_f32_e32 v167, v39, v167
	v_mul_f32_e32 v168, v40, v168
	v_mul_f32_e32 v169, v41, v169
	s_add_u32 s10, s3, 64
	s_lshl_b32 s11, s10, 12
	s_add_u32 s8, s68, s11
	s_addc_u32 s9, s69, 0
	global_store_dwordx4 v170, v[138:141], s[8:9] offset:0
	global_store_dwordx4 v170, v[142:145], s[8:9] offset:1024
	global_store_dwordx4 v170, v[146:149], s[8:9] offset:2048
	global_store_dwordx4 v170, v[150:153], s[8:9] offset:3072
	s_add_u32 s8, s8, 0x1000
	s_addc_u32 s9, s9, 0
	global_store_dwordx4 v170, v[154:157], s[8:9] offset:0
	global_store_dwordx4 v170, v[158:161], s[8:9] offset:1024
	global_store_dwordx4 v170, v[162:165], s[8:9] offset:2048
	global_store_dwordx4 v170, v[166:169], s[8:9] offset:3072
	s_add_u32 s10, s3, 96
	s_lshl_b32 s11, s10, 12
	s_add_u32 s4, s36, s11
	s_addc_u32 s5, s37, 0
	s_lshl_b32 s11, s10, 11
	s_add_u32 s11, s11, 0x5100000
	s_add_u32 s6, s70, s11
	s_addc_u32 s7, s71, 0
	global_load_dwordx4 v[42:45], v170, s[4:5] offset:0
	global_load_dwordx4 v[46:49], v170, s[4:5] offset:1024
	global_load_dwordx4 v[50:53], v170, s[4:5] offset:2048
	global_load_dwordx4 v[54:57], v170, s[4:5] offset:3072
	global_load_dwordx2 v[74:75], v171, s[6:7] offset:0
	global_load_dwordx2 v[76:77], v171, s[6:7] offset:512
	global_load_dwordx2 v[78:79], v171, s[6:7] offset:1024
	global_load_dwordx2 v[80:81], v171, s[6:7] offset:1536
	s_add_u32 s4, s4, 0x1000
	s_addc_u32 s5, s5, 0
	s_add_u32 s6, s6, 0x800
	s_addc_u32 s7, s7, 0
	global_load_dwordx4 v[58:61], v170, s[4:5] offset:0
	global_load_dwordx4 v[62:65], v170, s[4:5] offset:1024
	global_load_dwordx4 v[66:69], v170, s[4:5] offset:2048
	global_load_dwordx4 v[70:73], v170, s[4:5] offset:3072
	global_load_dwordx2 v[82:83], v171, s[6:7] offset:0
	global_load_dwordx2 v[84:85], v171, s[6:7] offset:512
	global_load_dwordx2 v[86:87], v171, s[6:7] offset:1024
	global_load_dwordx2 v[88:89], v171, s[6:7] offset:1536
	s_waitcnt vmcnt(24)
	v_lshlrev_b32_e32 v174, 16, v122
	v_fma_f32 v138, v10, v174, v90
	v_and_b32_e32 v174, 0xffff0000, v122
	v_fma_f32 v139, v11, v174, v91
	v_lshlrev_b32_e32 v174, 16, v123
	v_fma_f32 v140, v12, v174, v92
	v_and_b32_e32 v174, 0xffff0000, v123
	v_fma_f32 v141, v13, v174, v93
	v_lshlrev_b32_e32 v174, 16, v124
	v_fma_f32 v142, v14, v174, v94
	v_and_b32_e32 v174, 0xffff0000, v124
	v_fma_f32 v143, v15, v174, v95
	v_lshlrev_b32_e32 v174, 16, v125
	v_fma_f32 v144, v16, v174, v96
	v_and_b32_e32 v174, 0xffff0000, v125
	v_fma_f32 v145, v17, v174, v97
	v_lshlrev_b32_e32 v174, 16, v126
	v_fma_f32 v146, v18, v174, v98
	v_and_b32_e32 v174, 0xffff0000, v126
	v_fma_f32 v147, v19, v174, v99
	v_lshlrev_b32_e32 v174, 16, v127
	v_fma_f32 v148, v20, v174, v100
	v_and_b32_e32 v174, 0xffff0000, v127
	v_fma_f32 v149, v21, v174, v101
	v_lshlrev_b32_e32 v174, 16, v128
	v_fma_f32 v150, v22, v174, v102
	v_and_b32_e32 v174, 0xffff0000, v128
	v_fma_f32 v151, v23, v174, v103
	v_lshlrev_b32_e32 v174, 16, v129
	v_fma_f32 v152, v24, v174, v104
	v_and_b32_e32 v174, 0xffff0000, v129
	v_fma_f32 v153, v25, v174, v105
	v_mul_f32_e32 v172, v138, v138
	v_fmac_f32_e32 v172, v139, v139
	v_fmac_f32_e32 v172, v140, v140
	v_fmac_f32_e32 v172, v141, v141
	v_fmac_f32_e32 v172, v142, v142
	v_fmac_f32_e32 v172, v143, v143
	v_fmac_f32_e32 v172, v144, v144
	v_fmac_f32_e32 v172, v145, v145
	v_fmac_f32_e32 v172, v146, v146
	v_fmac_f32_e32 v172, v147, v147
	v_fmac_f32_e32 v172, v148, v148
	v_fmac_f32_e32 v172, v149, v149
	v_fmac_f32_e32 v172, v150, v150
	v_fmac_f32_e32 v172, v151, v151
	v_fmac_f32_e32 v172, v152, v152
	v_fmac_f32_e32 v172, v153, v153
	v_lshlrev_b32_e32 v174, 16, v130
	v_fma_f32 v154, v10, v174, v106
	v_and_b32_e32 v174, 0xffff0000, v130
	v_fma_f32 v155, v11, v174, v107
	v_lshlrev_b32_e32 v174, 16, v131
	v_fma_f32 v156, v12, v174, v108
	v_and_b32_e32 v174, 0xffff0000, v131
	v_fma_f32 v157, v13, v174, v109
	v_lshlrev_b32_e32 v174, 16, v132
	v_fma_f32 v158, v14, v174, v110
	v_and_b32_e32 v174, 0xffff0000, v132
	v_fma_f32 v159, v15, v174, v111
	v_lshlrev_b32_e32 v174, 16, v133
	v_fma_f32 v160, v16, v174, v112
	v_and_b32_e32 v174, 0xffff0000, v133
	v_fma_f32 v161, v17, v174, v113
	v_lshlrev_b32_e32 v174, 16, v134
	v_fma_f32 v162, v18, v174, v114
	v_and_b32_e32 v174, 0xffff0000, v134
	v_fma_f32 v163, v19, v174, v115
	v_lshlrev_b32_e32 v174, 16, v135
	v_fma_f32 v164, v20, v174, v116
	v_and_b32_e32 v174, 0xffff0000, v135
	v_fma_f32 v165, v21, v174, v117
	v_lshlrev_b32_e32 v174, 16, v136
	v_fma_f32 v166, v22, v174, v118
	v_and_b32_e32 v174, 0xffff0000, v136
	v_fma_f32 v167, v23, v174, v119
	v_lshlrev_b32_e32 v174, 16, v137
	v_fma_f32 v168, v24, v174, v120
	v_and_b32_e32 v174, 0xffff0000, v137
	v_fma_f32 v169, v25, v174, v121
	v_mul_f32_e32 v173, v154, v154
	v_fmac_f32_e32 v173, v155, v155
	v_fmac_f32_e32 v173, v156, v156
	v_fmac_f32_e32 v173, v157, v157
; __device__ void final_phase(const Params& p) {
;     ...
;                 s0 += h0[c][0] * h0[c][0] + h0[c][1] * h0[c][1] + h0[c][2] * h0[c][2] + h0[c][3] * h0[c][3];
;                 s1 += h1[c][0] * h1[c][0] + h1[c][1] * h1[c][1] + h1[c][2] * h1[c][2] + h1[c][3] * h1[c][3];
;             }
; #pragma unroll
;             for (int m = 32; m >= 1; m >>= 1) { s0 += __shfl_xor(s0, m); s1 += __shfl_xor(s1, m); }
;             const float rs0 = rsqrtf(s0 * (1.f / 1024.f) + EPS), rs1 = rsqrtf(s1 * (1.f / 1024.f) + EPS);
; #pragma unroll
;             for (int c = 0; c < 4; ++c) { *(f32x4*)(op + c * 256 + lane * 4) = h0[c] * rs0 * g[c]; *(f32x4*)(op + 1024 + c * 256 + lane * 4) = h1[c] * rs1 * g[c]; }
	v_fmac_f32_e32 v173, v158, v158
	v_fmac_f32_e32 v173, v159, v159
	v_fmac_f32_e32 v173, v160, v160
	v_fmac_f32_e32 v173, v161, v161
	v_fmac_f32_e32 v173, v162, v162
	v_fmac_f32_e32 v173, v163, v163
	v_fmac_f32_e32 v173, v164, v164
	v_fmac_f32_e32 v173, v165, v165
	v_fmac_f32_e32 v173, v166, v166
	v_fmac_f32_e32 v173, v167, v167
	v_fmac_f32_e32 v173, v168, v168
	v_fmac_f32_e32 v173, v169, v169
	s_nop 1
	v_add_f32_dpp v172, v172, v172 row_shr:1 row_mask:0xf bank_mask:0xf bound_ctrl:1
	s_nop 1
	v_add_f32_dpp v173, v173, v173 row_shr:1 row_mask:0xf bank_mask:0xf bound_ctrl:1
	s_nop 0
	v_add_f32_dpp v172, v172, v172 row_shr:2 row_mask:0xf bank_mask:0xf bound_ctrl:1
	v_add_f32_dpp v173, v173, v173 row_shr:2 row_mask:0xf bank_mask:0xf bound_ctrl:1
	s_nop 0
	v_add_f32_dpp v172, v172, v172 row_shr:4 row_mask:0xf bank_mask:0xf bound_ctrl:1
	v_add_f32_dpp v173, v173, v173 row_shr:4 row_mask:0xf bank_mask:0xf bound_ctrl:1
	s_nop 0
	v_add_f32_dpp v172, v172, v172 row_shr:8 row_mask:0xf bank_mask:0xf bound_ctrl:1
	v_add_f32_dpp v173, v173, v173 row_shr:8 row_mask:0xf bank_mask:0xf bound_ctrl:1
	s_nop 0
	v_readlane_b32 s12, v172, 15
	v_readlane_b32 s13, v172, 31
	v_readlane_b32 s14, v172, 47
	v_readlane_b32 s15, v172, 63
	v_readlane_b32 s16, v173, 15
	v_readlane_b32 s17, v173, 31
	v_readlane_b32 s18, v173, 47
	v_readlane_b32 s19, v173, 63
	s_nop 1
	v_mov_b32_e32 v172, s12
	v_add_f32_e32 v172, s13, v172
	v_add_f32_e32 v172, s14, v172
	v_add_f32_e32 v172, s15, v172
	v_mov_b32_e32 v173, s16
	v_add_f32_e32 v173, s17, v173
	v_add_f32_e32 v173, s18, v173
	v_add_f32_e32 v173, s19, v173
	v_mov_b32_e32 v174, 0x358637bd
	v_fmac_f32_e32 v174, 0x3a800000, v172
	v_rsq_f32_e32 v172, v174
	v_mov_b32_e32 v174, 0x358637bd
	v_fmac_f32_e32 v174, 0x3a800000, v173
	v_rsq_f32_e32 v173, v174
	s_nop 0
	v_mul_f32_e32 v138, v138, v172
	v_mul_f32_e32 v139, v139, v172
	v_mul_f32_e32 v140, v140, v172
	v_mul_f32_e32 v141, v141, v172
	v_mul_f32_e32 v142, v142, v172
	v_mul_f32_e32 v143, v143, v172
	v_mul_f32_e32 v144, v144, v172
	v_mul_f32_e32 v145, v145, v172
	v_mul_f32_e32 v146, v146, v172
	v_mul_f32_e32 v147, v147, v172
	v_mul_f32_e32 v148, v148, v172
	v_mul_f32_e32 v149, v149, v172
	v_mul_f32_e32 v150, v150, v172
	v_mul_f32_e32 v151, v151, v172
	v_mul_f32_e32 v152, v152, v172
	v_mul_f32_e32 v153, v153, v172
	v_mul_f32_e32 v138, v26, v138
	v_mul_f32_e32 v139, v27, v139
	v_mul_f32_e32 v140, v28, v140
	v_mul_f32_e32 v141, v29, v141
	v_mul_f32_e32 v142, v30, v142
	v_mul_f32_e32 v143, v31, v143
	v_mul_f32_e32 v144, v32, v144
	v_mul_f32_e32 v145, v33, v145
	v_mul_f32_e32 v146, v34, v146
	v_mul_f32_e32 v147, v35, v147
	v_mul_f32_e32 v148, v36, v148
	v_mul_f32_e32 v149, v37, v149
	v_mul_f32_e32 v150, v38, v150
	v_mul_f32_e32 v151, v39, v151
	v_mul_f32_e32 v152, v40, v152
	v_mul_f32_e32 v153, v41, v153
	v_mul_f32_e32 v154, v154, v173
	v_mul_f32_e32 v155, v155, v173
	v_mul_f32_e32 v156, v156, v173
	v_mul_f32_e32 v157, v157, v173
	v_mul_f32_e32 v158, v158, v173
	v_mul_f32_e32 v159, v159, v173
	v_mul_f32_e32 v160, v160, v173
	v_mul_f32_e32 v161, v161, v173
	v_mul_f32_e32 v162, v162, v173
	v_mul_f32_e32 v163, v163, v173
	v_mul_f32_e32 v164, v164, v173
	v_mul_f32_e32 v165, v165, v173
	v_mul_f32_e32 v166, v166, v173
	v_mul_f32_e32 v167, v167, v173
	v_mul_f32_e32 v168, v168, v173
	v_mul_f32_e32 v169, v169, v173
	v_mul_f32_e32 v154, v26, v154
	v_mul_f32_e32 v155, v27, v155
	v_mul_f32_e32 v156, v28, v156
	v_mul_f32_e32 v157, v29, v157
	v_mul_f32_e32 v158, v30, v158
	v_mul_f32_e32 v159, v31, v159
	v_mul_f32_e32 v160, v32, v160
	v_mul_f32_e32 v161, v33, v161
	v_mul_f32_e32 v162, v34, v162
	v_mul_f32_e32 v163, v35, v163
	v_mul_f32_e32 v164, v36, v164
	v_mul_f32_e32 v165, v37, v165
	v_mul_f32_e32 v166, v38, v166
	v_mul_f32_e32 v167, v39, v167
	v_mul_f32_e32 v168, v40, v168
	v_mul_f32_e32 v169, v41, v169
	s_add_u32 s10, s3, 80
	s_lshl_b32 s11, s10, 12
	s_add_u32 s8, s68, s11
	s_addc_u32 s9, s69, 0
	global_store_dwordx4 v170, v[138:141], s[8:9] offset:0
	global_store_dwordx4 v170, v[142:145], s[8:9] offset:1024
	global_store_dwordx4 v170, v[146:149], s[8:9] offset:2048
	global_store_dwordx4 v170, v[150:153], s[8:9] offset:3072
	s_add_u32 s8, s8, 0x1000
	s_addc_u32 s9, s9, 0
	global_store_dwordx4 v170, v[154:157], s[8:9] offset:0
	global_store_dwordx4 v170, v[158:161], s[8:9] offset:1024
	global_store_dwordx4 v170, v[162:165], s[8:9] offset:2048
	global_store_dwordx4 v170, v[166:169], s[8:9] offset:3072
	s_add_u32 s10, s3, 112
	s_lshl_b32 s11, s10, 12
	s_add_u32 s4, s36, s11
	s_addc_u32 s5, s37, 0
	s_lshl_b32 s11, s10, 11
	s_add_u32 s11, s11, 0x5100000
	s_add_u32 s6, s70, s11
	s_addc_u32 s7, s71, 0
	global_load_dwordx4 v[90:93], v170, s[4:5] offset:0
	global_load_dwordx4 v[94:97], v170, s[4:5] offset:1024
	global_load_dwordx4 v[98:101], v170, s[4:5] offset:2048
	global_load_dwordx4 v[102:105], v170, s[4:5] offset:3072
	global_load_dwordx2 v[122:123], v171, s[6:7] offset:0
	global_load_dwordx2 v[124:125], v171, s[6:7] offset:512
	global_load_dwordx2 v[126:127], v171, s[6:7] offset:1024
	global_load_dwordx2 v[128:129], v171, s[6:7] offset:1536
	s_add_u32 s4, s4, 0x1000
	s_addc_u32 s5, s5, 0
	s_add_u32 s6, s6, 0x800
	s_addc_u32 s7, s7, 0
	global_load_dwordx4 v[106:109], v170, s[4:5] offset:0
	global_load_dwordx4 v[110:113], v170, s[4:5] offset:1024
	global_load_dwordx4 v[114:117], v170, s[4:5] offset:2048
	global_load_dwordx4 v[118:121], v170, s[4:5] offset:3072
	global_load_dwordx2 v[130:131], v171, s[6:7] offset:0
	global_load_dwordx2 v[132:133], v171, s[6:7] offset:512
	global_load_dwordx2 v[134:135], v171, s[6:7] offset:1024
	global_load_dwordx2 v[136:137], v171, s[6:7] offset:1536
	s_waitcnt vmcnt(24)
; __device__ __forceinline__ float bf_lo(unsigned u) { return __uint_as_float(u << 16); }
; __device__ __forceinline__ float bf_hi(unsigned u) { return __uint_as_float(u & 0xffff0000u); }
; __device__ void final_phase(const Params& p) {
;     ...
;                 const f32x4 x0 = *(const f32x4*)(xp + c * 256 + lane * 4), x1 = *(const f32x4*)(xp + 1024 + c * 256 + lane * 4);
;                 const u32x2 y0 = *(const u32x2*)(yp + c * 256 + lane * 4), y1 = *(const u32x2*)(yp + 1024 + c * 256 + lane * 4);
;                 h0[c] = x0 + gt[c] * (f32x4){bf_lo(y0[0]), bf_hi(y0[0]), bf_lo(y0[1]), bf_hi(y0[1])};
;                 h1[c] = x1 + gt[c] * (f32x4){bf_lo(y1[0]), bf_hi(y1[0]), bf_lo(y1[1]), bf_hi(y1[1])};
;                 s0 += h0[c][0] * h0[c][0] + h0[c][1] * h0[c][1] + h0[c][2] * h0[c][2] + h0[c][3] * h0[c][3];
;                 s1 += h1[c][0] * h1[c][0] + h1[c][1] * h1[c][1] + h1[c][2] * h1[c][2] + h1[c][3] * h1[c][3];
;             }
; #pragma unroll
;             for (int m = 32; m >= 1; m >>= 1) { s0 += __shfl_xor(s0, m); s1 += __shfl_xor(s1, m); }
;             const float rs0 = rsqrtf(s0 * (1.f / 1024.f) + EPS), rs1 = rsqrtf(s1 * (1.f / 1024.f) + EPS);
; #pragma unroll
;             for (int c = 0; c < 4; ++c) { *(f32x4*)(op + c * 256 + lane * 4) = h0[c] * rs0 * g[c]; *(f32x4*)(op + 1024 + c * 256 + lane * 4) = h1[c] * rs1 * g[c]; }
	v_lshlrev_b32_e32 v174, 16, v74
	v_fma_f32 v138, v10, v174, v42
	v_and_b32_e32 v174, 0xffff0000, v74
	v_fma_f32 v139, v11, v174, v43
	v_lshlrev_b32_e32 v174, 16, v75
	v_fma_f32 v140, v12, v174, v44
	v_and_b32_e32 v174, 0xffff0000, v75
	v_fma_f32 v141, v13, v174, v45
	v_lshlrev_b32_e32 v174, 16, v76
	v_fma_f32 v142, v14, v174, v46
	v_and_b32_e32 v174, 0xffff0000, v76
	v_fma_f32 v143, v15, v174, v47
	v_lshlrev_b32_e32 v174, 16, v77
	v_fma_f32 v144, v16, v174, v48
	v_and_b32_e32 v174, 0xffff0000, v77
	v_fma_f32 v145, v17, v174, v49
	v_lshlrev_b32_e32 v174, 16, v78
	v_fma_f32 v146, v18, v174, v50
	v_and_b32_e32 v174, 0xffff0000, v78
	v_fma_f32 v147, v19, v174, v51
	v_lshlrev_b32_e32 v174, 16, v79
	v_fma_f32 v148, v20, v174, v52
	v_and_b32_e32 v174, 0xffff0000, v79
	v_fma_f32 v149, v21, v174, v53
	v_lshlrev_b32_e32 v174, 16, v80
	v_fma_f32 v150, v22, v174, v54
	v_and_b32_e32 v174, 0xffff0000, v80
	v_fma_f32 v151, v23, v174, v55
	v_lshlrev_b32_e32 v174, 16, v81
	v_fma_f32 v152, v24, v174, v56
	v_and_b32_e32 v174, 0xffff0000, v81
	v_fma_f32 v153, v25, v174, v57
	v_mul_f32_e32 v172, v138, v138
	v_fmac_f32_e32 v172, v139, v139
	v_fmac_f32_e32 v172, v140, v140
	v_fmac_f32_e32 v172, v141, v141
	v_fmac_f32_e32 v172, v142, v142
	v_fmac_f32_e32 v172, v143, v143
	v_fmac_f32_e32 v172, v144, v144
	v_fmac_f32_e32 v172, v145, v145
	v_fmac_f32_e32 v172, v146, v146
	v_fmac_f32_e32 v172, v147, v147
	v_fmac_f32_e32 v172, v148, v148
	v_fmac_f32_e32 v172, v149, v149
	v_fmac_f32_e32 v172, v150, v150
	v_fmac_f32_e32 v172, v151, v151
	v_fmac_f32_e32 v172, v152, v152
	v_fmac_f32_e32 v172, v153, v153
	v_lshlrev_b32_e32 v174, 16, v82
	v_fma_f32 v154, v10, v174, v58
	v_and_b32_e32 v174, 0xffff0000, v82
	v_fma_f32 v155, v11, v174, v59
	v_lshlrev_b32_e32 v174, 16, v83
	v_fma_f32 v156, v12, v174, v60
	v_and_b32_e32 v174, 0xffff0000, v83
	v_fma_f32 v157, v13, v174, v61
	v_lshlrev_b32_e32 v174, 16, v84
	v_fma_f32 v158, v14, v174, v62
	v_and_b32_e32 v174, 0xffff0000, v84
	v_fma_f32 v159, v15, v174, v63
	v_lshlrev_b32_e32 v174, 16, v85
	v_fma_f32 v160, v16, v174, v64
	v_and_b32_e32 v174, 0xffff0000, v85
	v_fma_f32 v161, v17, v174, v65
	v_lshlrev_b32_e32 v174, 16, v86
	v_fma_f32 v162, v18, v174, v66
	v_and_b32_e32 v174, 0xffff0000, v86
	v_fma_f32 v163, v19, v174, v67
	v_lshlrev_b32_e32 v174, 16, v87
	v_fma_f32 v164, v20, v174, v68
	v_and_b32_e32 v174, 0xffff0000, v87
	v_fma_f32 v165, v21, v174, v69
	v_lshlrev_b32_e32 v174, 16, v88
	v_fma_f32 v166, v22, v174, v70
	v_and_b32_e32 v174, 0xffff0000, v88
	v_fma_f32 v167, v23, v174, v71
	v_lshlrev_b32_e32 v174, 16, v89
	v_fma_f32 v168, v24, v174, v72
	v_and_b32_e32 v174, 0xffff0000, v89
	v_fma_f32 v169, v25, v174, v73
	v_mul_f32_e32 v173, v154, v154
	v_fmac_f32_e32 v173, v155, v155
	v_fmac_f32_e32 v173, v156, v156
	v_fmac_f32_e32 v173, v157, v157
	v_fmac_f32_e32 v173, v158, v158
	v_fmac_f32_e32 v173, v159, v159
	v_fmac_f32_e32 v173, v160, v160
	v_fmac_f32_e32 v173, v161, v161
	v_fmac_f32_e32 v173, v162, v162
	v_fmac_f32_e32 v173, v163, v163
	v_fmac_f32_e32 v173, v164, v164
	v_fmac_f32_e32 v173, v165, v165
	v_fmac_f32_e32 v173, v166, v166
	v_fmac_f32_e32 v173, v167, v167
	v_fmac_f32_e32 v173, v168, v168
	v_fmac_f32_e32 v173, v169, v169
	s_nop 1
	v_add_f32_dpp v172, v172, v172 row_shr:1 row_mask:0xf bank_mask:0xf bound_ctrl:1
	s_nop 1
	v_add_f32_dpp v173, v173, v173 row_shr:1 row_mask:0xf bank_mask:0xf bound_ctrl:1
	s_nop 0
	v_add_f32_dpp v172, v172, v172 row_shr:2 row_mask:0xf bank_mask:0xf bound_ctrl:1
	v_add_f32_dpp v173, v173, v173 row_shr:2 row_mask:0xf bank_mask:0xf bound_ctrl:1
	s_nop 0
	v_add_f32_dpp v172, v172, v172 row_shr:4 row_mask:0xf bank_mask:0xf bound_ctrl:1
	v_add_f32_dpp v173, v173, v173 row_shr:4 row_mask:0xf bank_mask:0xf bound_ctrl:1
	s_nop 0
	v_add_f32_dpp v172, v172, v172 row_shr:8 row_mask:0xf bank_mask:0xf bound_ctrl:1
	v_add_f32_dpp v173, v173, v173 row_shr:8 row_mask:0xf bank_mask:0xf bound_ctrl:1
	s_nop 0
	v_readlane_b32 s12, v172, 15
	v_readlane_b32 s13, v172, 31
	v_readlane_b32 s14, v172, 47
	v_readlane_b32 s15, v172, 63
	v_readlane_b32 s16, v173, 15
	v_readlane_b32 s17, v173, 31
	v_readlane_b32 s18, v173, 47
	v_readlane_b32 s19, v173, 63
	s_nop 1
	v_mov_b32_e32 v172, s12
	v_add_f32_e32 v172, s13, v172
	v_add_f32_e32 v172, s14, v172
	v_add_f32_e32 v172, s15, v172
	v_mov_b32_e32 v173, s16
	v_add_f32_e32 v173, s17, v173
	v_add_f32_e32 v173, s18, v173
	v_add_f32_e32 v173, s19, v173
	v_mov_b32_e32 v174, 0x358637bd
	v_fmac_f32_e32 v174, 0x3a800000, v172
	v_rsq_f32_e32 v172, v174
	v_mov_b32_e32 v174, 0x358637bd
	v_fmac_f32_e32 v174, 0x3a800000, v173
	v_rsq_f32_e32 v173, v174
	s_nop 0
	v_mul_f32_e32 v138, v138, v172
	v_mul_f32_e32 v139, v139, v172
	v_mul_f32_e32 v140, v140, v172
	v_mul_f32_e32 v141, v141, v172
	v_mul_f32_e32 v142, v142, v172
	v_mul_f32_e32 v143, v143, v172
	v_mul_f32_e32 v144, v144, v172
	v_mul_f32_e32 v145, v145, v172
	v_mul_f32_e32 v146, v146, v172
	v_mul_f32_e32 v147, v147, v172
	v_mul_f32_e32 v148, v148, v172
	v_mul_f32_e32 v149, v149, v172
	v_mul_f32_e32 v150, v150, v172
	v_mul_f32_e32 v151, v151, v172
	v_mul_f32_e32 v152, v152, v172
	v_mul_f32_e32 v153, v153, v172
	v_mul_f32_e32 v138, v26, v138
	v_mul_f32_e32 v139, v27, v139
	v_mul_f32_e32 v140, v28, v140
	v_mul_f32_e32 v141, v29, v141
	v_mul_f32_e32 v142, v30, v142
	v_mul_f32_e32 v143, v31, v143
	v_mul_f32_e32 v144, v32, v144
	v_mul_f32_e32 v145, v33, v145
	v_mul_f32_e32 v146, v34, v146
	v_mul_f32_e32 v147, v35, v147
	v_mul_f32_e32 v148, v36, v148
	v_mul_f32_e32 v149, v37, v149
	v_mul_f32_e32 v150, v38, v150
	v_mul_f32_e32 v151, v39, v151
	v_mul_f32_e32 v152, v40, v152
	v_mul_f32_e32 v153, v41, v153
	v_mul_f32_e32 v154, v154, v173
; __device__ __forceinline__ float bf_lo(unsigned u) { return __uint_as_float(u << 16); }
; __device__ __forceinline__ float bf_hi(unsigned u) { return __uint_as_float(u & 0xffff0000u); }
; __device__ void final_phase(const Params& p) {
;     ...
;                 const f32x4 x0 = *(const f32x4*)(xp + c * 256 + lane * 4), x1 = *(const f32x4*)(xp + 1024 + c * 256 + lane * 4);
;                 const u32x2 y0 = *(const u32x2*)(yp + c * 256 + lane * 4), y1 = *(const u32x2*)(yp + 1024 + c * 256 + lane * 4);
;                 h0[c] = x0 + gt[c] * (f32x4){bf_lo(y0[0]), bf_hi(y0[0]), bf_lo(y0[1]), bf_hi(y0[1])};
;                 h1[c] = x1 + gt[c] * (f32x4){bf_lo(y1[0]), bf_hi(y1[0]), bf_lo(y1[1]), bf_hi(y1[1])};
;                 s0 += h0[c][0] * h0[c][0] + h0[c][1] * h0[c][1] + h0[c][2] * h0[c][2] + h0[c][3] * h0[c][3];
;                 s1 += h1[c][0] * h1[c][0] + h1[c][1] * h1[c][1] + h1[c][2] * h1[c][2] + h1[c][3] * h1[c][3];
;             }
; #pragma unroll
;             for (int m = 32; m >= 1; m >>= 1) { s0 += __shfl_xor(s0, m); s1 += __shfl_xor(s1, m); }
;             const float rs0 = rsqrtf(s0 * (1.f / 1024.f) + EPS), rs1 = rsqrtf(s1 * (1.f / 1024.f) + EPS);
; #pragma unroll
;             for (int c = 0; c < 4; ++c) { *(f32x4*)(op + c * 256 + lane * 4) = h0[c] * rs0 * g[c]; *(f32x4*)(op + 1024 + c * 256 + lane * 4) = h1[c] * rs1 * g[c]; }
	v_mul_f32_e32 v155, v155, v173
	v_mul_f32_e32 v156, v156, v173
	v_mul_f32_e32 v157, v157, v173
	v_mul_f32_e32 v158, v158, v173
	v_mul_f32_e32 v159, v159, v173
	v_mul_f32_e32 v160, v160, v173
	v_mul_f32_e32 v161, v161, v173
	v_mul_f32_e32 v162, v162, v173
	v_mul_f32_e32 v163, v163, v173
	v_mul_f32_e32 v164, v164, v173
	v_mul_f32_e32 v165, v165, v173
	v_mul_f32_e32 v166, v166, v173
	v_mul_f32_e32 v167, v167, v173
	v_mul_f32_e32 v168, v168, v173
	v_mul_f32_e32 v169, v169, v173
	v_mul_f32_e32 v154, v26, v154
	v_mul_f32_e32 v155, v27, v155
	v_mul_f32_e32 v156, v28, v156
	v_mul_f32_e32 v157, v29, v157
	v_mul_f32_e32 v158, v30, v158
	v_mul_f32_e32 v159, v31, v159
	v_mul_f32_e32 v160, v32, v160
	v_mul_f32_e32 v161, v33, v161
	v_mul_f32_e32 v162, v34, v162
	v_mul_f32_e32 v163, v35, v163
	v_mul_f32_e32 v164, v36, v164
	v_mul_f32_e32 v165, v37, v165
	v_mul_f32_e32 v166, v38, v166
	v_mul_f32_e32 v167, v39, v167
	v_mul_f32_e32 v168, v40, v168
	v_mul_f32_e32 v169, v41, v169
	s_add_u32 s10, s3, 96
	s_lshl_b32 s11, s10, 12
	s_add_u32 s8, s68, s11
	s_addc_u32 s9, s69, 0
	global_store_dwordx4 v170, v[138:141], s[8:9] offset:0
	global_store_dwordx4 v170, v[142:145], s[8:9] offset:1024
	global_store_dwordx4 v170, v[146:149], s[8:9] offset:2048
	global_store_dwordx4 v170, v[150:153], s[8:9] offset:3072
	s_add_u32 s8, s8, 0x1000
	s_addc_u32 s9, s9, 0
	global_store_dwordx4 v170, v[154:157], s[8:9] offset:0
	global_store_dwordx4 v170, v[158:161], s[8:9] offset:1024
	global_store_dwordx4 v170, v[162:165], s[8:9] offset:2048
	global_store_dwordx4 v170, v[166:169], s[8:9] offset:3072
	s_waitcnt vmcnt(8)
	v_lshlrev_b32_e32 v174, 16, v122
	v_fma_f32 v138, v10, v174, v90
	v_and_b32_e32 v174, 0xffff0000, v122
	v_fma_f32 v139, v11, v174, v91
	v_lshlrev_b32_e32 v174, 16, v123
	v_fma_f32 v140, v12, v174, v92
	v_and_b32_e32 v174, 0xffff0000, v123
	v_fma_f32 v141, v13, v174, v93
	v_lshlrev_b32_e32 v174, 16, v124
	v_fma_f32 v142, v14, v174, v94
	v_and_b32_e32 v174, 0xffff0000, v124
	v_fma_f32 v143, v15, v174, v95
	v_lshlrev_b32_e32 v174, 16, v125
	v_fma_f32 v144, v16, v174, v96
	v_and_b32_e32 v174, 0xffff0000, v125
	v_fma_f32 v145, v17, v174, v97
	v_lshlrev_b32_e32 v174, 16, v126
	v_fma_f32 v146, v18, v174, v98
	v_and_b32_e32 v174, 0xffff0000, v126
	v_fma_f32 v147, v19, v174, v99
	v_lshlrev_b32_e32 v174, 16, v127
	v_fma_f32 v148, v20, v174, v100
	v_and_b32_e32 v174, 0xffff0000, v127
	v_fma_f32 v149, v21, v174, v101
	v_lshlrev_b32_e32 v174, 16, v128
	v_fma_f32 v150, v22, v174, v102
	v_and_b32_e32 v174, 0xffff0000, v128
	v_fma_f32 v151, v23, v174, v103
	v_lshlrev_b32_e32 v174, 16, v129
	v_fma_f32 v152, v24, v174, v104
	v_and_b32_e32 v174, 0xffff0000, v129
	v_fma_f32 v153, v25, v174, v105
	v_mul_f32_e32 v172, v138, v138
	v_fmac_f32_e32 v172, v139, v139
	v_fmac_f32_e32 v172, v140, v140
	v_fmac_f32_e32 v172, v141, v141
	v_fmac_f32_e32 v172, v142, v142
	v_fmac_f32_e32 v172, v143, v143
	v_fmac_f32_e32 v172, v144, v144
	v_fmac_f32_e32 v172, v145, v145
	v_fmac_f32_e32 v172, v146, v146
	v_fmac_f32_e32 v172, v147, v147
	v_fmac_f32_e32 v172, v148, v148
	v_fmac_f32_e32 v172, v149, v149
	v_fmac_f32_e32 v172, v150, v150
	v_fmac_f32_e32 v172, v151, v151
	v_fmac_f32_e32 v172, v152, v152
	v_fmac_f32_e32 v172, v153, v153
	v_lshlrev_b32_e32 v174, 16, v130
	v_fma_f32 v154, v10, v174, v106
	v_and_b32_e32 v174, 0xffff0000, v130
	v_fma_f32 v155, v11, v174, v107
	v_lshlrev_b32_e32 v174, 16, v131
	v_fma_f32 v156, v12, v174, v108
	v_and_b32_e32 v174, 0xffff0000, v131
	v_fma_f32 v157, v13, v174, v109
	v_lshlrev_b32_e32 v174, 16, v132
	v_fma_f32 v158, v14, v174, v110
	v_and_b32_e32 v174, 0xffff0000, v132
	v_fma_f32 v159, v15, v174, v111
	v_lshlrev_b32_e32 v174, 16, v133
	v_fma_f32 v160, v16, v174, v112
	v_and_b32_e32 v174, 0xffff0000, v133
	v_fma_f32 v161, v17, v174, v113
	v_lshlrev_b32_e32 v174, 16, v134
	v_fma_f32 v162, v18, v174, v114
	v_and_b32_e32 v174, 0xffff0000, v134
	v_fma_f32 v163, v19, v174, v115
	v_lshlrev_b32_e32 v174, 16, v135
	v_fma_f32 v164, v20, v174, v116
	v_and_b32_e32 v174, 0xffff0000, v135
	v_fma_f32 v165, v21, v174, v117
	v_lshlrev_b32_e32 v174, 16, v136
	v_fma_f32 v166, v22, v174, v118
	v_and_b32_e32 v174, 0xffff0000, v136
	v_fma_f32 v167, v23, v174, v119
	v_lshlrev_b32_e32 v174, 16, v137
	v_fma_f32 v168, v24, v174, v120
	v_and_b32_e32 v174, 0xffff0000, v137
	v_fma_f32 v169, v25, v174, v121
	v_mul_f32_e32 v173, v154, v154
	v_fmac_f32_e32 v173, v155, v155
	v_fmac_f32_e32 v173, v156, v156
	v_fmac_f32_e32 v173, v157, v157
	v_fmac_f32_e32 v173, v158, v158
	v_fmac_f32_e32 v173, v159, v159
	v_fmac_f32_e32 v173, v160, v160
	v_fmac_f32_e32 v173, v161, v161
	v_fmac_f32_e32 v173, v162, v162
	v_fmac_f32_e32 v173, v163, v163
	v_fmac_f32_e32 v173, v164, v164
	v_fmac_f32_e32 v173, v165, v165
	v_fmac_f32_e32 v173, v166, v166
	v_fmac_f32_e32 v173, v167, v167
	v_fmac_f32_e32 v173, v168, v168
	v_fmac_f32_e32 v173, v169, v169
	s_nop 1
	v_add_f32_dpp v172, v172, v172 row_shr:1 row_mask:0xf bank_mask:0xf bound_ctrl:1
	s_nop 1
	v_add_f32_dpp v173, v173, v173 row_shr:1 row_mask:0xf bank_mask:0xf bound_ctrl:1
	s_nop 0
	v_add_f32_dpp v172, v172, v172 row_shr:2 row_mask:0xf bank_mask:0xf bound_ctrl:1
	v_add_f32_dpp v173, v173, v173 row_shr:2 row_mask:0xf bank_mask:0xf bound_ctrl:1
	s_nop 0
	v_add_f32_dpp v172, v172, v172 row_shr:4 row_mask:0xf bank_mask:0xf bound_ctrl:1
; __device__ void final_phase(const Params& p) {
;     const int tid = threadIdx.x, w = tid >> 6, lane = tid & 63;
;     const float* modp = (const float*)(p.ws + WS_MODP);
;     const bf16_t* Y = (const bf16_t*)(p.ws + WS_QF);
;     const int rows_per = NLAT / gridDim.x;
;     for (int r0 = blockIdx.x * rows_per; r0 < NLAT; r0 += gridDim.x * rows_per) {
;         const int rend = min(r0 + rows_per, NLAT);
;         int curb = -1; f32x4 gt[4], g[4];
; #pragma unroll
;         for (int c = 0; c < 4; ++c) { g[c] = *(const f32x4*)(p.final_norm_g + c * 256 + lane * 4); gt[c] = (f32x4){0.f, 0.f, 0.f, 0.f}; }
;         for (int row = r0 + w * 2; row < rend; row += 16) {
;     ...
;             for (int m = 32; m >= 1; m >>= 1) { s0 += __shfl_xor(s0, m); s1 += __shfl_xor(s1, m); }
;             const float rs0 = rsqrtf(s0 * (1.f / 1024.f) + EPS), rs1 = rsqrtf(s1 * (1.f / 1024.f) + EPS);
; #pragma unroll
;             for (int c = 0; c < 4; ++c) { *(f32x4*)(op + c * 256 + lane * 4) = h0[c] * rs0 * g[c]; *(f32x4*)(op + 1024 + c * 256 + lane * 4) = h1[c] * rs1 * g[c]; }
	v_add_f32_dpp v173, v173, v173 row_shr:4 row_mask:0xf bank_mask:0xf bound_ctrl:1
	s_nop 0
	v_add_f32_dpp v172, v172, v172 row_shr:8 row_mask:0xf bank_mask:0xf bound_ctrl:1
	v_add_f32_dpp v173, v173, v173 row_shr:8 row_mask:0xf bank_mask:0xf bound_ctrl:1
	s_nop 0
	v_readlane_b32 s12, v172, 15
	v_readlane_b32 s13, v172, 31
	v_readlane_b32 s14, v172, 47
	v_readlane_b32 s15, v172, 63
	v_readlane_b32 s16, v173, 15
	v_readlane_b32 s17, v173, 31
	v_readlane_b32 s18, v173, 47
	v_readlane_b32 s19, v173, 63
	s_nop 1
	v_mov_b32_e32 v172, s12
	v_add_f32_e32 v172, s13, v172
	v_add_f32_e32 v172, s14, v172
	v_add_f32_e32 v172, s15, v172
	v_mov_b32_e32 v173, s16
	v_add_f32_e32 v173, s17, v173
	v_add_f32_e32 v173, s18, v173
	v_add_f32_e32 v173, s19, v173
	v_mov_b32_e32 v174, 0x358637bd
	v_fmac_f32_e32 v174, 0x3a800000, v172
	v_rsq_f32_e32 v172, v174
	v_mov_b32_e32 v174, 0x358637bd
	v_fmac_f32_e32 v174, 0x3a800000, v173
	v_rsq_f32_e32 v173, v174
	s_nop 0
	v_mul_f32_e32 v138, v138, v172
	v_mul_f32_e32 v139, v139, v172
	v_mul_f32_e32 v140, v140, v172
	v_mul_f32_e32 v141, v141, v172
	v_mul_f32_e32 v142, v142, v172
	v_mul_f32_e32 v143, v143, v172
	v_mul_f32_e32 v144, v144, v172
	v_mul_f32_e32 v145, v145, v172
	v_mul_f32_e32 v146, v146, v172
	v_mul_f32_e32 v147, v147, v172
	v_mul_f32_e32 v148, v148, v172
	v_mul_f32_e32 v149, v149, v172
	v_mul_f32_e32 v150, v150, v172
	v_mul_f32_e32 v151, v151, v172
	v_mul_f32_e32 v152, v152, v172
	v_mul_f32_e32 v153, v153, v172
	v_mul_f32_e32 v138, v26, v138
	v_mul_f32_e32 v139, v27, v139
	v_mul_f32_e32 v140, v28, v140
	v_mul_f32_e32 v141, v29, v141
	v_mul_f32_e32 v142, v30, v142
	v_mul_f32_e32 v143, v31, v143
	v_mul_f32_e32 v144, v32, v144
	v_mul_f32_e32 v145, v33, v145
	v_mul_f32_e32 v146, v34, v146
	v_mul_f32_e32 v147, v35, v147
	v_mul_f32_e32 v148, v36, v148
	v_mul_f32_e32 v149, v37, v149
	v_mul_f32_e32 v150, v38, v150
	v_mul_f32_e32 v151, v39, v151
	v_mul_f32_e32 v152, v40, v152
	v_mul_f32_e32 v153, v41, v153
	v_mul_f32_e32 v154, v154, v173
	v_mul_f32_e32 v155, v155, v173
	v_mul_f32_e32 v156, v156, v173
	v_mul_f32_e32 v157, v157, v173
	v_mul_f32_e32 v158, v158, v173
	v_mul_f32_e32 v159, v159, v173
	v_mul_f32_e32 v160, v160, v173
	v_mul_f32_e32 v161, v161, v173
	v_mul_f32_e32 v162, v162, v173
	v_mul_f32_e32 v163, v163, v173
	v_mul_f32_e32 v164, v164, v173
	v_mul_f32_e32 v165, v165, v173
	v_mul_f32_e32 v166, v166, v173
	v_mul_f32_e32 v167, v167, v173
	v_mul_f32_e32 v168, v168, v173
	v_mul_f32_e32 v169, v169, v173
	v_mul_f32_e32 v154, v26, v154
	v_mul_f32_e32 v155, v27, v155
	v_mul_f32_e32 v156, v28, v156
	v_mul_f32_e32 v157, v29, v157
	v_mul_f32_e32 v158, v30, v158
	v_mul_f32_e32 v159, v31, v159
	v_mul_f32_e32 v160, v32, v160
	v_mul_f32_e32 v161, v33, v161
	v_mul_f32_e32 v162, v34, v162
	v_mul_f32_e32 v163, v35, v163
	v_mul_f32_e32 v164, v36, v164
	v_mul_f32_e32 v165, v37, v165
	v_mul_f32_e32 v166, v38, v166
	v_mul_f32_e32 v167, v39, v167
	v_mul_f32_e32 v168, v40, v168
	v_mul_f32_e32 v169, v41, v169
	s_add_u32 s10, s3, 112
	s_lshl_b32 s11, s10, 12
	s_add_u32 s8, s68, s11
	s_addc_u32 s9, s69, 0
	global_store_dwordx4 v170, v[138:141], s[8:9] offset:0
	global_store_dwordx4 v170, v[142:145], s[8:9] offset:1024
	global_store_dwordx4 v170, v[146:149], s[8:9] offset:2048
	global_store_dwordx4 v170, v[150:153], s[8:9] offset:3072
	s_add_u32 s8, s8, 0x1000
	s_addc_u32 s9, s9, 0
	global_store_dwordx4 v170, v[154:157], s[8:9] offset:0
	global_store_dwordx4 v170, v[158:161], s[8:9] offset:1024
	global_store_dwordx4 v170, v[162:165], s[8:9] offset:2048
	global_store_dwordx4 v170, v[166:169], s[8:9] offset:3072
	s_branch .LBB0_518
.Lp6_orig:
	s_load_dword s0, s[0:1], 0x98
	s_waitcnt lgkmcnt(0)
	v_cvt_f32_u32_e32 v1, s0
	s_sub_i32 s1, 0, s0
	v_rcp_iflag_f32_e32 v1, v1
	s_nop 0
	v_mul_f32_e32 v1, 0x4f7ffffe, v1
	v_cvt_u32_f32_e32 v1, v1
	s_nop 0
	v_readfirstlane_b32 s3, v1
	s_mul_i32 s1, s1, s3
	s_mul_hi_u32 s1, s3, s1
	s_add_i32 s3, s3, s1
	s_lshr_b32 s1, s3, 17
	s_mul_i32 s3, s1, s0
	s_sub_i32 s3, 0x8000, s3
	s_add_i32 s4, s1, 1
	s_sub_i32 s5, s3, s0
	s_cmp_ge_u32 s3, s0
	s_cselect_b32 s1, s4, s1
	s_cselect_b32 s3, s5, s3
	s_add_i32 s4, s1, 1
	s_cmp_ge_u32 s3, s0
	s_cselect_b32 s3, s4, s1
	s_mul_i32 s12, s3, s2
	s_cmpk_gt_i32 s12, 0x7fff
	s_cbranch_scc1 .LBB0_518
	v_lshlrev_b32_e32 v1, 2, v0
	s_waitcnt vmcnt(0)
	v_and_b32_e32 v2, 0xfc, v1
	v_mov_b32_e32 v33, 0
	v_lshlrev_b32_e32 v32, 2, v2
	v_and_b32_e32 v3, 63, v0
	v_lshrrev_b32_e32 v1, 5, v0
	s_mul_i32 s13, s3, s0
	v_lshl_add_u64 v[34:35], s[66:67], 0, v[32:33]
	v_lshl_add_u64 v[4:5], s[48:49], 0, v[32:33]
	s_mov_b64 s[0:1], 0x2000
	v_lshlrev_b32_e32 v32, 3, v3
	v_and_b32_e32 v45, 14, v1
	v_lshl_add_u64 v[36:37], v[4:5], 0, s[0:1]
	v_lshl_add_u64 v[0:1], s[70:71], 0, v[32:33]
	s_mov_b64 s[0:1], 0x5100000
	v_lshl_add_u64 v[38:39], v[0:1], 0, s[0:1]
	v_mbcnt_lo_u32_b32 v0, -1, 0
	v_mbcnt_hi_u32_b32 v52, -1, v0
	v_and_b32_e32 v0, 64, v52
	v_add_u32_e32 v40, s12, v45
	v_lshlrev_b32_e32 v42, 4, v3
	v_mov_b32_e32 v43, v33
	v_lshlrev_b32_e32 v32, 2, v2
	s_movk_i32 s14, 0x1000
	s_mov_b32 s2, 0x3a800000
	s_mov_b32 s15, 0x800000
	s_mov_b64 s[4:5], 0x8000
	s_mov_b64 s[6:7], 0x10000
	v_add_u32_e32 v53, 64, v0
	v_xor_b32_e32 v54, 32, v52
	v_xor_b32_e32 v55, 16, v52
	v_xor_b32_e32 v56, 8, v52
	v_xor_b32_e32 v57, 4, v52
	v_xor_b32_e32 v58, 2, v52
	v_xor_b32_e32 v59, 1, v52
	v_mov_b32_e32 v44, 0x358637bd
	s_branch .LBB0_513
